# peeled first K-tile waits vmcnt(24) instead of vmcnt(8): same load guarantees, epilogue store acks not required until the third phase
# speedup vs baseline: 1.0030x; 1.0005x over previous
; #define PG8_STAGE(bufoff, gbase, voff) do { _Pragma("unroll") for (int _i = 0; _i < 2; ++_i) \
;         __builtin_amdgcn_global_load_lds((const unsigned*)((const char*)(gbase) + (voff)[_i]), (LAS unsigned*)(lds + (bufoff) + ldsw + _i * 8192), 16, 0, 0); } while (0)
; #define PG8_LDA(dst, b, h) do { _Pragma("unroll") for (int m = 0; m < 4; ++m) _Pragma("unroll") for (int k = 0; k < 2; ++k) dst[m][k] = *(const LAS bf16x8*)(lds + PG8_SA(b, h) + aoff + m * 2048 + k * 1024); } while (0)
; #define PG8_LDB(dst, b, h) do { _Pragma("unroll") for (int n = 0; n < 2; ++n) _Pragma("unroll") for (int k = 0; k < 2; ++k) dst[n][k] = *(const LAS bf16x8*)(lds + PG8_SB(b, h) + boff + n * 2048 + k * 1024); } while (0)
; #define PG8_WAIT_V(n) asm volatile("s_waitcnt vmcnt(" #n ")" ::: "memory")
; #define PG8_WAIT_L(n) asm volatile("s_waitcnt lgkmcnt(" #n ")" ::: "memory")
; #define PG8_BAR __builtin_amdgcn_s_barrier()
; template <class Epi, class Sched, bool ALIGN_EPI>
; __device__ __forceinline__ void gemm_phase(LAS unsigned char* lds, const int wid, const int lda_, const int ldb_, const int K_, const Sched& S, const Epi& E) {
;     ...
;     PG8_STAGE(PG8_SB(0, 0), cB, voffB); PG8_STAGE(PG8_SB(0, 1), cB + hstepB, voffB); PG8_STAGE(PG8_SA(0, 0), cA, voffA); PG8_STAGE(PG8_SA(0, 1), cA + hstepA, voffA);
;     if (wr == 1) PG8_BAR;
;     PG8_WAIT_V(2); PG8_BAR;
;     PG8_STAGE(PG8_SB(1, 0), cB + kstep, voffB); PG8_STAGE(PG8_SA(1, 0), cA + kstep, voffA); PG8_STAGE(PG8_SB(1, 1), cB + hstepB + kstep, voffB);
;     PG8_WAIT_V(6); PG8_BAR;
;     for (;;) {
;         const bool has_next = S.next(ui + 1, nxt);
;         const int nt = S.nt(cur);
;         const char* nA = has_next ? S.a(nxt) : cA; const char* nB = has_next ? S.b(nxt) : cB;
; #pragma unroll 1
;         for (int t = 0; t < nt; t += 2) {
;             const bool last = (t == nt - 2);
;             const char* a1 = cA + (size_t)(t + 1) * kstep;
;             const char* a2 = last ? nA : cA + (size_t)(t + 2) * kstep; const char* b2 = last ? nB : cB + (size_t)(t + 2) * kstep;
;             const char* a3 = a2 + kstep; const char* b3 = b2 + kstep;
;             PG8_LDB(B0, 0, 0); PG8_LDB(B1, 0, 1); PG8_SCHED; PG8_LDA(At, 0, 0); PG8_STAGE(PG8_SA(1, 1), a1 + hstepA, voffA);
;             PG8_WAIT_V(8); PG8_WAIT_L(0); PG8_BAR; PG8_MMA(0, 0, At, B0); PG8_MMA(0, 1, At, B1); PG8_BAR; PG8_SCHED;
.LBB0_298:
	s_ashr_i32 s37, s36, 31
	s_xor_b64 s[40:41], s[4:5], -1
	s_lshl_b64 s[38:39], s[36:37], 20
	v_readlane_b32 s42, v253, 52
	v_readlane_b32 s43, v253, 53
	s_add_u32 s38, s42, s38
	s_addc_u32 s39, s43, s39
	s_and_b64 s[42:43], s[4:5], exec
	s_cselect_b32 s31, s39, s47
	s_cselect_b32 s37, s38, s46
	s_ashr_i32 s35, s34, 31
	s_lshl_b64 s[42:43], s[34:35], 20
	s_add_u32 s42, s7, s42
	s_addc_u32 s43, s14, s43
	s_and_b64 s[4:5], s[4:5], exec
	s_cselect_b32 s4, s43, s49
	s_cselect_b32 s5, s42, s48
	s_add_u32 s50, s46, 0x80
	s_addc_u32 s51, s47, 0
	s_add_u32 s35, s48, 0x100
	v_lshl_add_u64 v[156:157], s[50:51], 0, v[152:153]
	v_lshl_add_u64 v[158:159], s[50:51], 0, v[154:155]
	s_addc_u32 s45, s49, 0
	s_mov_b32 s76, -2
	s_mov_b64 s[48:49], 0
	s_add_u32 s17, s46, s48
	s_addc_u32 s27, s47, s49
	s_add_u32 s17, s17, 0x100
	s_addc_u32 s27, s27, 0
	s_add_u32 s77, s35, s48
	s_addc_u32 s78, s45, s49
	s_add_i32 s80, 0, 0x10000
	s_cmpk_eq_i32 s48, 0xf00
	s_cselect_b32 s51, s31, s27
	s_cselect_b32 s50, s37, s17
	v_add_u32_e32 v141, s80, v135
	s_cselect_b32 s79, s4, s78
	s_cselect_b32 s78, s5, s77
	s_add_i32 s17, 0, 0x14000
	ds_read_b128 v[160:163], v141
	ds_read_b128 v[164:167], v141 offset:1024
	ds_read_b128 v[168:171], v141 offset:2048
	ds_read_b128 v[172:175], v141 offset:3072
	v_add_u32_e32 v141, s17, v135
	ds_read_b128 v[180:183], v141
	ds_read_b128 v[184:187], v141 offset:1024
	ds_read_b128 v[188:191], v141 offset:2048
	ds_read_b128 v[192:195], v141 offset:3072
	v_lshl_add_u64 v[228:229], v[158:159], 0, s[48:49]
	s_add_i32 m0, s16, 0xc000
	ds_read_b128 v[196:199], v139
	ds_read_b128 v[200:203], v139 offset:1024
	ds_read_b128 v[204:207], v139 offset:2048
	ds_read_b128 v[208:211], v139 offset:3072
	ds_read_b128 v[212:215], v139 offset:4096
	ds_read_b128 v[216:219], v139 offset:5120
	ds_read_b128 v[220:223], v139 offset:6144
	ds_read_b128 v[224:227], v139 offset:7168
	global_load_lds_dwordx4 v[228:229], off
	v_lshl_add_u64 v[228:229], v[156:157], 0, s[48:49]
	s_add_i32 m0, s16, 0xe000
	s_nop 0
	global_load_lds_dwordx4 v[228:229], off
	s_waitcnt vmcnt(24)
	s_waitcnt lgkmcnt(0)
	s_barrier
	s_setprio 1
	s_waitcnt lgkmcnt(0)
	v_mfma_f32_16x16x32_bf16 v[124:127], v[160:163], v[196:199], 0
	v_mfma_f32_16x16x32_bf16 v[120:123], v[168:171], v[196:199], 0
	v_mfma_f32_16x16x32_bf16 v[116:119], v[160:163], v[204:207], 0
	v_mfma_f32_16x16x32_bf16 v[112:115], v[168:171], v[204:207], 0
	v_mfma_f32_16x16x32_bf16 v[100:103], v[160:163], v[212:215], 0
	v_mfma_f32_16x16x32_bf16 v[96:99], v[168:171], v[212:215], 0
	v_mfma_f32_16x16x32_bf16 v[84:87], v[160:163], v[220:223], 0
	v_mfma_f32_16x16x32_bf16 v[80:83], v[168:171], v[220:223], 0
	v_mfma_f32_16x16x32_bf16 v[124:127], v[164:167], v[200:203], v[124:127]
	v_mfma_f32_16x16x32_bf16 v[120:123], v[172:175], v[200:203], v[120:123]
	v_mfma_f32_16x16x32_bf16 v[116:119], v[164:167], v[208:211], v[116:119]
	v_mfma_f32_16x16x32_bf16 v[112:115], v[172:175], v[208:211], v[112:115]
	v_mfma_f32_16x16x32_bf16 v[100:103], v[164:167], v[216:219], v[100:103]
	v_mfma_f32_16x16x32_bf16 v[96:99], v[172:175], v[216:219], v[96:99]
	v_mfma_f32_16x16x32_bf16 v[84:87], v[164:167], v[224:227], v[84:87]
	v_mfma_f32_16x16x32_bf16 v[80:83], v[172:175], v[224:227], v[80:83]
	s_setprio 0
	s_setprio 1
	v_mfma_f32_16x16x32_bf16 v[108:111], v[180:183], v[196:199], 0
	v_mfma_f32_16x16x32_bf16 v[104:107], v[188:191], v[196:199], 0
	v_mfma_f32_16x16x32_bf16 v[92:95], v[180:183], v[204:207], 0
	v_mfma_f32_16x16x32_bf16 v[88:91], v[188:191], v[204:207], 0
	v_mfma_f32_16x16x32_bf16 v[76:79], v[180:183], v[212:215], 0
	v_mfma_f32_16x16x32_bf16 v[72:75], v[188:191], v[212:215], 0
	v_mfma_f32_16x16x32_bf16 v[68:71], v[180:183], v[220:223], 0
	v_mfma_f32_16x16x32_bf16 v[64:67], v[188:191], v[220:223], 0
	v_mfma_f32_16x16x32_bf16 v[108:111], v[184:187], v[200:203], v[108:111]
	v_mfma_f32_16x16x32_bf16 v[104:107], v[192:195], v[200:203], v[104:107]
	v_mfma_f32_16x16x32_bf16 v[92:95], v[184:187], v[208:211], v[92:95]
	v_mfma_f32_16x16x32_bf16 v[88:91], v[192:195], v[208:211], v[88:91]
	v_mfma_f32_16x16x32_bf16 v[76:79], v[184:187], v[216:219], v[76:79]
	v_mfma_f32_16x16x32_bf16 v[72:75], v[192:195], v[216:219], v[72:75]
	v_mfma_f32_16x16x32_bf16 v[68:71], v[184:187], v[224:227], v[68:71]
	v_mfma_f32_16x16x32_bf16 v[64:67], v[192:195], v[224:227], v[64:67]
	s_setprio 0
	s_barrier
; #define PG8_STAGE(bufoff, gbase, voff) do { _Pragma("unroll") for (int _i = 0; _i < 2; ++_i) \
;         __builtin_amdgcn_global_load_lds((const unsigned*)((const char*)(gbase) + (voff)[_i]), (LAS unsigned*)(lds + (bufoff) + ldsw + _i * 8192), 16, 0, 0); } while (0)
; #define PG8_LDA(dst, b, h) do { _Pragma("unroll") for (int m = 0; m < 4; ++m) _Pragma("unroll") for (int k = 0; k < 2; ++k) dst[m][k] = *(const LAS bf16x8*)(lds + PG8_SA(b, h) + aoff + m * 2048 + k * 1024); } while (0)
; #define PG8_MMA(ai, bj, At, Bt) do { __builtin_amdgcn_s_setprio(1); _Pragma("unroll") for (int m = 0; m < 4; ++m) _Pragma("unroll") for (int n = 0; n < 2; ++n) _Pragma("unroll") for (int k = 0; k < 2; ++k) \
;         acc[ai][bj][m][n] = __builtin_amdgcn_mfma_f32_16x16x32_bf16(Bt[n][k], At[m][k], acc[ai][bj][m][n], 0, 0, 0); __builtin_amdgcn_s_setprio(0); } while (0)
; #define PG8_WAIT_V(n) asm volatile("s_waitcnt vmcnt(" #n ")" ::: "memory")
; #define PG8_WAIT_L(n) asm volatile("s_waitcnt lgkmcnt(" #n ")" ::: "memory")
; #define PG8_BAR __builtin_amdgcn_s_barrier()
; #define PG8_SCHED __builtin_amdgcn_sched_barrier(0)
; template <class Epi, class Sched, bool ALIGN_EPI>
; __device__ __forceinline__ void gemm_phase(LAS unsigned char* lds, const int wid, const int lda_, const int ldb_, const int K_, const Sched& S, const Epi& E) {
;     ...
;             PG8_LDA(At, 0, 1); PG8_STAGE(PG8_SB(0, 0), b2, voffB); PG8_STAGE(PG8_SB(0, 1), b2 + hstepB, voffB); PG8_STAGE(PG8_SA(0, 0), a2, voffA);
;             PG8_WAIT_V(8); PG8_WAIT_L(0); PG8_BAR; PG8_MMA(1, 0, At, B0); PG8_MMA(1, 1, At, B1); PG8_BAR; PG8_SCHED;
	s_add_i32 s27, s80, s3
	v_lshl_add_u64 v[228:229], s[78:79], 0, v[176:177]
	s_mov_b32 m0, s27
	ds_read_b128 v[196:199], v139 offset:16384
	ds_read_b128 v[200:203], v139 offset:17408
	ds_read_b128 v[204:207], v139 offset:18432
	ds_read_b128 v[208:211], v139 offset:19456
	ds_read_b128 v[212:215], v139 offset:20480
	ds_read_b128 v[216:219], v139 offset:21504
	ds_read_b128 v[220:223], v139 offset:22528
	ds_read_b128 v[224:227], v139 offset:23552
	global_load_lds_dwordx4 v[228:229], off
	s_add_i32 m0, s27, 0x2000
	v_lshl_add_u64 v[230:231], s[78:79], 0, v[128:129]
	s_add_u32 s78, s78, s10
	s_addc_u32 s79, s79, s11
	s_add_i32 s17, s17, s3
	global_load_lds_dwordx4 v[230:231], off
	v_lshl_add_u64 v[232:233], s[78:79], 0, v[176:177]
	s_mov_b32 m0, s17
	v_lshl_add_u64 v[234:235], s[78:79], 0, v[128:129]
	global_load_lds_dwordx4 v[232:233], off
	s_add_i32 m0, s17, 0x2000
	v_lshl_add_u64 v[236:237], s[50:51], 0, v[132:133]
	global_load_lds_dwordx4 v[234:235], off
	s_mov_b32 m0, s16
	v_lshl_add_u64 v[246:247], s[50:51], 0, v[130:131]
	global_load_lds_dwordx4 v[236:237], off
	s_mov_b32 m0, s15
	s_nop 0
	global_load_lds_dwordx4 v[246:247], off
	s_waitcnt vmcnt(24)
	s_waitcnt lgkmcnt(0)
	s_barrier
	s_setprio 1
	s_waitcnt lgkmcnt(0)
	v_mfma_f32_16x16x32_bf16 v[60:63], v[160:163], v[196:199], 0
	v_mfma_f32_16x16x32_bf16 v[56:59], v[168:171], v[196:199], 0
	v_mfma_f32_16x16x32_bf16 v[52:55], v[160:163], v[204:207], 0
	v_mfma_f32_16x16x32_bf16 v[48:51], v[168:171], v[204:207], 0
	v_mfma_f32_16x16x32_bf16 v[36:39], v[160:163], v[212:215], 0
	v_mfma_f32_16x16x32_bf16 v[32:35], v[168:171], v[212:215], 0
	v_mfma_f32_16x16x32_bf16 v[20:23], v[160:163], v[220:223], 0
	v_mfma_f32_16x16x32_bf16 v[16:19], v[168:171], v[220:223], 0
	v_mfma_f32_16x16x32_bf16 v[60:63], v[164:167], v[200:203], v[60:63]
	v_mfma_f32_16x16x32_bf16 v[56:59], v[172:175], v[200:203], v[56:59]
	v_mfma_f32_16x16x32_bf16 v[52:55], v[164:167], v[208:211], v[52:55]
	v_mfma_f32_16x16x32_bf16 v[48:51], v[172:175], v[208:211], v[48:51]
	v_mfma_f32_16x16x32_bf16 v[36:39], v[164:167], v[216:219], v[36:39]
	v_mfma_f32_16x16x32_bf16 v[32:35], v[172:175], v[216:219], v[32:35]
	v_mfma_f32_16x16x32_bf16 v[20:23], v[164:167], v[224:227], v[20:23]
	v_mfma_f32_16x16x32_bf16 v[16:19], v[172:175], v[224:227], v[16:19]
	s_setprio 0
	s_setprio 1
	v_mfma_f32_16x16x32_bf16 v[44:47], v[180:183], v[196:199], 0
	v_mfma_f32_16x16x32_bf16 v[40:43], v[188:191], v[196:199], 0
	v_mfma_f32_16x16x32_bf16 v[28:31], v[180:183], v[204:207], 0
	v_mfma_f32_16x16x32_bf16 v[24:27], v[188:191], v[204:207], 0
	v_mfma_f32_16x16x32_bf16 v[12:15], v[180:183], v[212:215], 0
	v_mfma_f32_16x16x32_bf16 v[8:11], v[188:191], v[212:215], 0
	v_mfma_f32_16x16x32_bf16 v[4:7], v[180:183], v[220:223], 0
	v_mfma_f32_16x16x32_bf16 v[0:3], v[188:191], v[220:223], 0
	v_mfma_f32_16x16x32_bf16 v[44:47], v[184:187], v[200:203], v[44:47]
	v_mfma_f32_16x16x32_bf16 v[40:43], v[192:195], v[200:203], v[40:43]
	v_mfma_f32_16x16x32_bf16 v[28:31], v[184:187], v[208:211], v[28:31]
	v_mfma_f32_16x16x32_bf16 v[24:27], v[192:195], v[208:211], v[24:27]
	v_mfma_f32_16x16x32_bf16 v[12:15], v[184:187], v[216:219], v[12:15]
	v_mfma_f32_16x16x32_bf16 v[8:11], v[192:195], v[216:219], v[8:11]
	v_mfma_f32_16x16x32_bf16 v[4:7], v[184:187], v[224:227], v[4:7]
	v_mfma_f32_16x16x32_bf16 v[0:3], v[192:195], v[224:227], v[0:3]
	s_setprio 0
	s_barrier
	s_branch .Lgemm_join_299

; #define PG8_STAGE(bufoff, gbase, voff) do { _Pragma("unroll") for (int _i = 0; _i < 2; ++_i) \
;         __builtin_amdgcn_global_load_lds((const unsigned*)((const char*)(gbase) + (voff)[_i]), (LAS unsigned*)(lds + (bufoff) + ldsw + _i * 8192), 16, 0, 0); } while (0)
; #define PG8_LDA(dst, b, h) do { _Pragma("unroll") for (int m = 0; m < 4; ++m) _Pragma("unroll") for (int k = 0; k < 2; ++k) dst[m][k] = *(const LAS bf16x8*)(lds + PG8_SA(b, h) + aoff + m * 2048 + k * 1024); } while (0)
; #define PG8_LDB(dst, b, h) do { _Pragma("unroll") for (int n = 0; n < 2; ++n) _Pragma("unroll") for (int k = 0; k < 2; ++k) dst[n][k] = *(const LAS bf16x8*)(lds + PG8_SB(b, h) + boff + n * 2048 + k * 1024); } while (0)
; #define PG8_WAIT_V(n) asm volatile("s_waitcnt vmcnt(" #n ")" ::: "memory")
; #define PG8_WAIT_L(n) asm volatile("s_waitcnt lgkmcnt(" #n ")" ::: "memory")
; #define PG8_BAR __builtin_amdgcn_s_barrier()
; template <class Epi, class Sched, bool ALIGN_EPI>
; __device__ __forceinline__ void gemm_phase(LAS unsigned char* lds, const int wid, const int lda_, const int ldb_, const int K_, const Sched& S, const Epi& E) {
;     ...
;     PG8_STAGE(PG8_SB(0, 0), cB, voffB); PG8_STAGE(PG8_SB(0, 1), cB + hstepB, voffB); PG8_STAGE(PG8_SA(0, 0), cA, voffA); PG8_STAGE(PG8_SA(0, 1), cA + hstepA, voffA);
;     if (wr == 1) PG8_BAR;
;     PG8_WAIT_V(2); PG8_BAR;
;     PG8_STAGE(PG8_SB(1, 0), cB + kstep, voffB); PG8_STAGE(PG8_SA(1, 0), cA + kstep, voffA); PG8_STAGE(PG8_SB(1, 1), cB + hstepB + kstep, voffB);
;     PG8_WAIT_V(6); PG8_BAR;
;     for (;;) {
;         const bool has_next = S.next(ui + 1, nxt);
;         const int nt = S.nt(cur);
;         const char* nA = has_next ? S.a(nxt) : cA; const char* nB = has_next ? S.b(nxt) : cB;
; #pragma unroll 1
;         for (int t = 0; t < nt; t += 2) {
;             const bool last = (t == nt - 2);
;             const char* a1 = cA + (size_t)(t + 1) * kstep;
;             const char* a2 = last ? nA : cA + (size_t)(t + 2) * kstep; const char* b2 = last ? nB : cB + (size_t)(t + 2) * kstep;
;             const char* a3 = a2 + kstep; const char* b3 = b2 + kstep;
;             PG8_LDB(B0, 0, 0); PG8_LDB(B1, 0, 1); PG8_SCHED; PG8_LDA(At, 0, 0); PG8_STAGE(PG8_SA(1, 1), a1 + hstepA, voffA);
;             PG8_WAIT_V(8); PG8_WAIT_L(0); PG8_BAR; PG8_MMA(0, 0, At, B0); PG8_MMA(0, 1, At, B1); PG8_BAR; PG8_SCHED;
.LBB0_670:
	s_xor_b64 s[44:45], s[4:5], -1
	s_cmp_gt_i32 s38, -1
	s_cselect_b64 s[50:51], -1, 0
	s_cmp_lt_i32 s38, 0
	s_cselect_b32 s35, 64, 16
	s_max_i32 s17, s75, 0
	s_ashr_i32 s43, s42, 31
	s_lshl_b32 s17, s17, 11
	s_lshl_b64 s[46:47], s[42:43], 21
	v_readlane_b32 s48, v252, 62
	v_readlane_b32 s49, v252, 63
	s_add_u32 s27, s48, s46
	s_addc_u32 s37, s49, s47
	s_add_u32 s46, s27, s17
	s_addc_u32 s47, s37, 0
	s_and_b64 s[48:49], s[4:5], exec
	s_cselect_b32 s37, s47, s95
	s_cselect_b32 s39, s46, s94
	s_ashr_i32 s41, s40, 31
	s_lshl_b64 s[48:49], s[40:41], 21
	s_add_u32 s27, s6, s48
	s_addc_u32 s41, s7, s49
	s_add_u32 s48, s27, s17
	s_addc_u32 s49, s41, 0
	s_and_b64 s[4:5], s[4:5], exec
	s_cselect_b32 s4, s49, s97
	s_cselect_b32 s5, s48, s96
	s_add_i32 s41, s35, -2
	s_add_u32 s94, s94, 0x80
	s_addc_u32 s95, s95, 0
	s_add_u32 s43, s96, 0x100
	s_mov_b32 s77, 0
	s_addc_u32 s76, s97, 0
	s_add_i32 s78, s77, 2
	s_add_u32 s17, s94, 0x80
	s_addc_u32 s27, s95, 0
	s_add_i32 s79, 0, 0x10000
	s_cmp_eq_u32 s41, s77
	s_cselect_b32 s97, s37, s27
	s_cselect_b32 s96, s39, s17
	v_add_u32_e32 v141, s79, v135
	s_cselect_b32 s81, s4, s76
	s_cselect_b32 s80, s5, s43
	s_add_i32 s17, 0, 0x14000
	ds_read_b128 v[156:159], v141
	ds_read_b128 v[160:163], v141 offset:1024
	ds_read_b128 v[164:167], v141 offset:2048
	ds_read_b128 v[168:171], v141 offset:3072
	v_add_u32_e32 v141, s17, v135
	ds_read_b128 v[172:175], v141
	ds_read_b128 v[180:183], v141 offset:1024
	ds_read_b128 v[184:187], v141 offset:2048
	ds_read_b128 v[188:191], v141 offset:3072
	v_lshl_add_u64 v[224:225], s[94:95], 0, v[152:153]
	s_add_i32 m0, s16, 0xc000
	ds_read_b128 v[192:195], v139
	ds_read_b128 v[196:199], v139 offset:1024
	ds_read_b128 v[200:203], v139 offset:2048
	ds_read_b128 v[204:207], v139 offset:3072
	ds_read_b128 v[208:211], v139 offset:4096
	ds_read_b128 v[212:215], v139 offset:5120
	ds_read_b128 v[216:219], v139 offset:6144
	ds_read_b128 v[220:223], v139 offset:7168
	global_load_lds_dwordx4 v[224:225], off
	v_lshl_add_u64 v[224:225], s[94:95], 0, v[154:155]
	s_add_i32 m0, s16, 0xe000
	s_nop 0
	global_load_lds_dwordx4 v[224:225], off
	s_waitcnt vmcnt(24)
	s_waitcnt lgkmcnt(0)
	s_barrier
	s_setprio 1
	s_waitcnt lgkmcnt(0)
	v_mfma_f32_16x16x32_bf16 v[124:127], v[156:159], v[192:195], 0
	v_mfma_f32_16x16x32_bf16 v[120:123], v[164:167], v[192:195], 0
	v_mfma_f32_16x16x32_bf16 v[116:119], v[156:159], v[200:203], 0
	v_mfma_f32_16x16x32_bf16 v[112:115], v[164:167], v[200:203], 0
	v_mfma_f32_16x16x32_bf16 v[100:103], v[156:159], v[208:211], 0
	v_mfma_f32_16x16x32_bf16 v[96:99], v[164:167], v[208:211], 0
	v_mfma_f32_16x16x32_bf16 v[84:87], v[156:159], v[216:219], 0
	v_mfma_f32_16x16x32_bf16 v[80:83], v[164:167], v[216:219], 0
	v_mfma_f32_16x16x32_bf16 v[124:127], v[160:163], v[196:199], v[124:127]
	v_mfma_f32_16x16x32_bf16 v[120:123], v[168:171], v[196:199], v[120:123]
	v_mfma_f32_16x16x32_bf16 v[116:119], v[160:163], v[204:207], v[116:119]
	v_mfma_f32_16x16x32_bf16 v[112:115], v[168:171], v[204:207], v[112:115]
	v_mfma_f32_16x16x32_bf16 v[100:103], v[160:163], v[212:215], v[100:103]
	v_mfma_f32_16x16x32_bf16 v[96:99], v[168:171], v[212:215], v[96:99]
	v_mfma_f32_16x16x32_bf16 v[84:87], v[160:163], v[220:223], v[84:87]
	v_mfma_f32_16x16x32_bf16 v[80:83], v[168:171], v[220:223], v[80:83]
	s_setprio 0
	s_setprio 1
	v_mfma_f32_16x16x32_bf16 v[108:111], v[172:175], v[192:195], 0
	v_mfma_f32_16x16x32_bf16 v[104:107], v[184:187], v[192:195], 0
	v_mfma_f32_16x16x32_bf16 v[92:95], v[172:175], v[200:203], 0
	v_mfma_f32_16x16x32_bf16 v[88:91], v[184:187], v[200:203], 0
	v_mfma_f32_16x16x32_bf16 v[76:79], v[172:175], v[208:211], 0
	v_mfma_f32_16x16x32_bf16 v[72:75], v[184:187], v[208:211], 0
	v_mfma_f32_16x16x32_bf16 v[68:71], v[172:175], v[216:219], 0
	v_mfma_f32_16x16x32_bf16 v[64:67], v[184:187], v[216:219], 0
	v_mfma_f32_16x16x32_bf16 v[108:111], v[180:183], v[196:199], v[108:111]
	v_mfma_f32_16x16x32_bf16 v[104:107], v[188:191], v[196:199], v[104:107]
	v_mfma_f32_16x16x32_bf16 v[92:95], v[180:183], v[204:207], v[92:95]
	v_mfma_f32_16x16x32_bf16 v[88:91], v[188:191], v[204:207], v[88:91]
	v_mfma_f32_16x16x32_bf16 v[76:79], v[180:183], v[212:215], v[76:79]
	v_mfma_f32_16x16x32_bf16 v[72:75], v[188:191], v[212:215], v[72:75]
	v_mfma_f32_16x16x32_bf16 v[68:71], v[180:183], v[220:223], v[68:71]
	v_mfma_f32_16x16x32_bf16 v[64:67], v[188:191], v[220:223], v[64:67]
	s_setprio 0
	s_barrier
; #define PG8_STAGE(bufoff, gbase, voff) do { _Pragma("unroll") for (int _i = 0; _i < 2; ++_i) \
;         __builtin_amdgcn_global_load_lds((const unsigned*)((const char*)(gbase) + (voff)[_i]), (LAS unsigned*)(lds + (bufoff) + ldsw + _i * 8192), 16, 0, 0); } while (0)
; #define PG8_LDA(dst, b, h) do { _Pragma("unroll") for (int m = 0; m < 4; ++m) _Pragma("unroll") for (int k = 0; k < 2; ++k) dst[m][k] = *(const LAS bf16x8*)(lds + PG8_SA(b, h) + aoff + m * 2048 + k * 1024); } while (0)
; #define PG8_MMA(ai, bj, At, Bt) do { __builtin_amdgcn_s_setprio(1); _Pragma("unroll") for (int m = 0; m < 4; ++m) _Pragma("unroll") for (int n = 0; n < 2; ++n) _Pragma("unroll") for (int k = 0; k < 2; ++k) \
;         acc[ai][bj][m][n] = __builtin_amdgcn_mfma_f32_16x16x32_bf16(Bt[n][k], At[m][k], acc[ai][bj][m][n], 0, 0, 0); __builtin_amdgcn_s_setprio(0); } while (0)
; #define PG8_WAIT_V(n) asm volatile("s_waitcnt vmcnt(" #n ")" ::: "memory")
; #define PG8_WAIT_L(n) asm volatile("s_waitcnt lgkmcnt(" #n ")" ::: "memory")
; #define PG8_BAR __builtin_amdgcn_s_barrier()
; #define PG8_SCHED __builtin_amdgcn_sched_barrier(0)
; template <class Epi, class Sched, bool ALIGN_EPI>
; __device__ __forceinline__ void gemm_phase(LAS unsigned char* lds, const int wid, const int lda_, const int ldb_, const int K_, const Sched& S, const Epi& E) {
;     ...
;             PG8_LDA(At, 0, 1); PG8_STAGE(PG8_SB(0, 0), b2, voffB); PG8_STAGE(PG8_SB(0, 1), b2 + hstepB, voffB); PG8_STAGE(PG8_SA(0, 0), a2, voffA);
;             PG8_WAIT_V(8); PG8_WAIT_L(0); PG8_BAR; PG8_MMA(1, 0, At, B0); PG8_MMA(1, 1, At, B1); PG8_BAR; PG8_SCHED;
	s_add_i32 s27, s79, s3
	v_lshl_add_u64 v[224:225], s[80:81], 0, v[176:177]
	s_mov_b32 m0, s27
	ds_read_b128 v[192:195], v139 offset:16384
	ds_read_b128 v[196:199], v139 offset:17408
	ds_read_b128 v[200:203], v139 offset:18432
	ds_read_b128 v[204:207], v139 offset:19456
	ds_read_b128 v[208:211], v139 offset:20480
	ds_read_b128 v[212:215], v139 offset:21504
	ds_read_b128 v[216:219], v139 offset:22528
	ds_read_b128 v[220:223], v139 offset:23552
	global_load_lds_dwordx4 v[224:225], off
	s_add_i32 m0, s27, 0x2000
	v_lshl_add_u64 v[226:227], s[80:81], 0, v[132:133]
	s_add_u32 s80, s80, s30
	s_addc_u32 s81, s81, s31
	s_add_i32 s17, s17, s3
	global_load_lds_dwordx4 v[226:227], off
	v_lshl_add_u64 v[228:229], s[80:81], 0, v[176:177]
	s_mov_b32 m0, s17
	v_lshl_add_u64 v[230:231], s[80:81], 0, v[132:133]
	global_load_lds_dwordx4 v[228:229], off
	s_add_i32 m0, s17, 0x2000
	v_lshl_add_u64 v[232:233], s[96:97], 0, v[128:129]
	global_load_lds_dwordx4 v[230:231], off
	s_mov_b32 m0, s16
	v_lshl_add_u64 v[234:235], s[96:97], 0, v[130:131]
	global_load_lds_dwordx4 v[232:233], off
	s_mov_b32 m0, s14
	s_nop 0
	global_load_lds_dwordx4 v[234:235], off
	s_waitcnt vmcnt(24)
	s_waitcnt lgkmcnt(0)
	s_barrier
	s_setprio 1
	s_waitcnt lgkmcnt(0)
	v_mfma_f32_16x16x32_bf16 v[60:63], v[156:159], v[192:195], 0
	v_mfma_f32_16x16x32_bf16 v[56:59], v[164:167], v[192:195], 0
	v_mfma_f32_16x16x32_bf16 v[52:55], v[156:159], v[200:203], 0
	v_mfma_f32_16x16x32_bf16 v[48:51], v[164:167], v[200:203], 0
	v_mfma_f32_16x16x32_bf16 v[36:39], v[156:159], v[208:211], 0
	v_mfma_f32_16x16x32_bf16 v[32:35], v[164:167], v[208:211], 0
	v_mfma_f32_16x16x32_bf16 v[20:23], v[156:159], v[216:219], 0
	v_mfma_f32_16x16x32_bf16 v[16:19], v[164:167], v[216:219], 0
	v_mfma_f32_16x16x32_bf16 v[60:63], v[160:163], v[196:199], v[60:63]
	v_mfma_f32_16x16x32_bf16 v[56:59], v[168:171], v[196:199], v[56:59]
	v_mfma_f32_16x16x32_bf16 v[52:55], v[160:163], v[204:207], v[52:55]
	v_mfma_f32_16x16x32_bf16 v[48:51], v[168:171], v[204:207], v[48:51]
	v_mfma_f32_16x16x32_bf16 v[36:39], v[160:163], v[212:215], v[36:39]
	v_mfma_f32_16x16x32_bf16 v[32:35], v[168:171], v[212:215], v[32:35]
	v_mfma_f32_16x16x32_bf16 v[20:23], v[160:163], v[220:223], v[20:23]
	v_mfma_f32_16x16x32_bf16 v[16:19], v[168:171], v[220:223], v[16:19]
	s_setprio 0
	s_setprio 1
	v_mfma_f32_16x16x32_bf16 v[44:47], v[172:175], v[192:195], 0
	v_mfma_f32_16x16x32_bf16 v[40:43], v[184:187], v[192:195], 0
	v_mfma_f32_16x16x32_bf16 v[28:31], v[172:175], v[200:203], 0
	v_mfma_f32_16x16x32_bf16 v[24:27], v[184:187], v[200:203], 0
	v_mfma_f32_16x16x32_bf16 v[12:15], v[172:175], v[208:211], 0
	v_mfma_f32_16x16x32_bf16 v[8:11], v[184:187], v[208:211], 0
	v_mfma_f32_16x16x32_bf16 v[4:7], v[172:175], v[216:219], 0
	v_mfma_f32_16x16x32_bf16 v[0:3], v[184:187], v[216:219], 0
	v_mfma_f32_16x16x32_bf16 v[44:47], v[180:183], v[196:199], v[44:47]
	v_mfma_f32_16x16x32_bf16 v[40:43], v[188:191], v[196:199], v[40:43]
	v_mfma_f32_16x16x32_bf16 v[28:31], v[180:183], v[204:207], v[28:31]
	v_mfma_f32_16x16x32_bf16 v[24:27], v[188:191], v[204:207], v[24:27]
	v_mfma_f32_16x16x32_bf16 v[12:15], v[180:183], v[212:215], v[12:15]
	v_mfma_f32_16x16x32_bf16 v[8:11], v[188:191], v[212:215], v[8:11]
	v_mfma_f32_16x16x32_bf16 v[4:7], v[180:183], v[220:223], v[4:7]
	v_mfma_f32_16x16x32_bf16 v[0:3], v[188:191], v[220:223], v[0:3]
	s_setprio 0
	s_barrier
	s_branch .Lgemm_join_671

; #define PG8_STAGE(bufoff, gbase, voff) do { _Pragma("unroll") for (int _i = 0; _i < 2; ++_i) \
;         __builtin_amdgcn_global_load_lds((const unsigned*)((const char*)(gbase) + (voff)[_i]), (LAS unsigned*)(lds + (bufoff) + ldsw + _i * 8192), 16, 0, 0); } while (0)
; #define PG8_LDA(dst, b, h) do { _Pragma("unroll") for (int m = 0; m < 4; ++m) _Pragma("unroll") for (int k = 0; k < 2; ++k) dst[m][k] = *(const LAS bf16x8*)(lds + PG8_SA(b, h) + aoff + m * 2048 + k * 1024); } while (0)
; #define PG8_WAIT_V(n) asm volatile("s_waitcnt vmcnt(" #n ")" ::: "memory")
; #define PG8_WAIT_L(n) asm volatile("s_waitcnt lgkmcnt(" #n ")" ::: "memory")
; template <class Epi, class Sched, bool ALIGN_EPI>
; __device__ __forceinline__ void gemm_phase(LAS unsigned char* lds, const int wid, const int lda_, const int ldb_, const int K_, const Sched& S, const Epi& E) {
;     ...
;     PG8_STAGE(PG8_SB(0, 0), cB, voffB); PG8_STAGE(PG8_SB(0, 1), cB + hstepB, voffB); PG8_STAGE(PG8_SA(0, 0), cA, voffA); PG8_STAGE(PG8_SA(0, 1), cA + hstepA, voffA);
;     if (wr == 1) PG8_BAR;
;     PG8_WAIT_V(2); PG8_BAR;
;     PG8_STAGE(PG8_SB(1, 0), cB + kstep, voffB); PG8_STAGE(PG8_SA(1, 0), cA + kstep, voffA); PG8_STAGE(PG8_SB(1, 1), cB + hstepB + kstep, voffB);
;     PG8_WAIT_V(6); PG8_BAR;
;     for (;;) {
;         const bool has_next = S.next(ui + 1, nxt);
;         const int nt = S.nt(cur);
;         const char* nA = has_next ? S.a(nxt) : cA; const char* nB = has_next ? S.b(nxt) : cB;
; #pragma unroll 1
;         for (int t = 0; t < nt; t += 2) {
;             const bool last = (t == nt - 2);
;             const char* a1 = cA + (size_t)(t + 1) * kstep;
;             const char* a2 = last ? nA : cA + (size_t)(t + 2) * kstep; const char* b2 = last ? nB : cB + (size_t)(t + 2) * kstep;
;             const char* a3 = a2 + kstep; const char* b3 = b2 + kstep;
;             PG8_LDB(B0, 0, 0); PG8_LDB(B1, 0, 1); PG8_SCHED; PG8_LDA(At, 0, 0); PG8_STAGE(PG8_SA(1, 1), a1 + hstepA, voffA);
;             PG8_WAIT_V(8); PG8_WAIT_L(0); PG8_BAR; PG8_MMA(0, 0, At, B0); PG8_MMA(0, 1, At, B1); PG8_BAR; PG8_SCHED;
;     __device__ __forceinline__ const char* a(const pg8::Unit& u) const { return (const char*)ws + WS_W1 + (size_t)(u.pm & 1) * 256 * 256 * 2; }
;     __device__ __forceinline__ const char* b(const pg8::Unit& u) const { return (const char*)ws + WS_A + ((size_t)u.pn * 256 * D + (size_t)(u.pm >> 1) * 256) * 2; }
.LBB0_696:
	v_mov_b64_e32 v[0:1], 0x480
	v_cmp_lt_i64_e32 vcc, s[4:5], v[0:1]
	s_lshl_b32 s4, s73, 17
	s_and_b32 s4, s4, 0x20000
	v_readlane_b32 s5, v253, 31
	s_add_u32 s34, s5, s4
	v_readlane_b32 s4, v253, 32
	s_addc_u32 s35, s4, 0
	s_and_b64 s[4:5], vcc, exec
	s_cselect_b32 s4, s35, s45
	s_cselect_b32 s5, s34, s44
	s_ashr_i32 s36, s73, 1
	s_ashr_i32 s31, s30, 31
	s_ashr_i32 s37, s36, 31
	s_lshl_b64 s[36:37], s[36:37], 9
	s_lshl_b64 s[42:43], s[30:31], 20
	v_readlane_b32 s46, v253, 52
	v_readlane_b32 s47, v253, 53
	s_add_u32 s31, s46, s42
	s_addc_u32 s42, s47, s43
	s_add_u32 s36, s31, s36
	s_addc_u32 s37, s42, s37
	s_and_b64 s[42:43], vcc, exec
	s_cselect_b32 s31, s37, s41
	s_cselect_b32 s76, s36, s40
	s_mov_b64 s[50:51], 0
	s_mov_b64 s[46:47], -1
	s_mov_b64 s[48:49], 0
	s_add_u32 s77, s44, s50
	s_addc_u32 s78, s45, s51
	s_add_u32 s79, s77, 0x100
	s_addc_u32 s80, s78, 0
	s_and_b64 s[42:43], s[48:49], exec
	s_cselect_b32 s95, s4, s80
	s_cselect_b32 s94, s5, s79
	s_add_u32 s42, s40, s50
	s_addc_u32 s43, s41, s51
	s_add_u32 s50, s42, 0x100
	s_addc_u32 s51, s43, 0
	s_add_i32 s93, 0, 0x10000
	s_and_b64 s[42:43], s[48:49], exec
	s_cselect_b32 s51, s31, s51
	s_cselect_b32 s50, s76, s50
	s_add_i32 s42, 0, 0x14000
	v_add_u32_e32 v141, s93, v135
	s_add_u32 vcc_lo, s77, s0
	ds_read_b128 v[152:155], v141
	ds_read_b128 v[156:159], v141 offset:1024
	ds_read_b128 v[160:163], v141 offset:2048
	ds_read_b128 v[164:167], v141 offset:3072
	v_add_u32_e32 v141, s42, v135
	s_addc_u32 vcc_hi, s78, s1
	s_add_i32 s87, s93, s3
	ds_read_b128 v[168:171], v141
	ds_read_b128 v[172:175], v141 offset:1024
	ds_read_b128 v[180:183], v141 offset:2048
	ds_read_b128 v[184:187], v141 offset:3072
	s_add_i32 m0, s16, 0xc000
	s_add_i32 s27, s16, 0xe000
	s_add_i32 s80, s87, 0x2000
	s_add_u32 s96, s50, s10
	s_addc_u32 s97, s51, s11
	s_add_i32 s86, s42, s3
	s_add_i32 s81, s86, 0x2000
	s_add_i32 s79, 0, 0x18000
	s_add_i32 s78, 0, 0x1c000
	s_add_u32 s48, s94, s0
	s_addc_u32 s49, s95, s1
	s_add_i32 s77, s79, s3
	s_add_i32 s93, s78, s3
	s_add_i32 s43, s77, 0x2000
	s_add_i32 s42, s93, 0x2000
	v_lshl_add_u64 v[220:221], vcc, 0, v[132:133]
	v_lshl_add_u64 v[220:221], v[220:221], 0, s[24:25]
	ds_read_b128 v[188:191], v139
	ds_read_b128 v[192:195], v139 offset:1024
	ds_read_b128 v[196:199], v139 offset:2048
	ds_read_b128 v[200:203], v139 offset:3072
	ds_read_b128 v[204:207], v139 offset:4096
	ds_read_b128 v[208:211], v139 offset:5120
	ds_read_b128 v[212:215], v139 offset:6144
	ds_read_b128 v[216:219], v139 offset:7168
	global_load_lds_dwordx4 v[220:221], off
	v_lshl_add_u64 v[220:221], vcc, 0, v[130:131]
	v_lshl_add_u64 v[220:221], v[220:221], 0, s[24:25]
	s_mov_b32 m0, s27
	s_nop 0
	global_load_lds_dwordx4 v[220:221], off
	s_waitcnt vmcnt(24)
	s_waitcnt lgkmcnt(0)
	s_barrier
	s_setprio 1
	s_waitcnt lgkmcnt(0)
	v_mfma_f32_16x16x32_bf16 v[124:127], v[152:155], v[188:191], 0
	v_mfma_f32_16x16x32_bf16 v[120:123], v[160:163], v[188:191], 0
	v_mfma_f32_16x16x32_bf16 v[116:119], v[152:155], v[196:199], 0
	v_mfma_f32_16x16x32_bf16 v[112:115], v[160:163], v[196:199], 0
	v_mfma_f32_16x16x32_bf16 v[100:103], v[152:155], v[204:207], 0
	v_mfma_f32_16x16x32_bf16 v[96:99], v[160:163], v[204:207], 0
	v_mfma_f32_16x16x32_bf16 v[84:87], v[152:155], v[212:215], 0
	v_mfma_f32_16x16x32_bf16 v[80:83], v[160:163], v[212:215], 0
	v_mfma_f32_16x16x32_bf16 v[124:127], v[156:159], v[192:195], v[124:127]
	v_mfma_f32_16x16x32_bf16 v[120:123], v[164:167], v[192:195], v[120:123]
	v_mfma_f32_16x16x32_bf16 v[116:119], v[156:159], v[200:203], v[116:119]
	v_mfma_f32_16x16x32_bf16 v[112:115], v[164:167], v[200:203], v[112:115]
	v_mfma_f32_16x16x32_bf16 v[100:103], v[156:159], v[208:211], v[100:103]
	v_mfma_f32_16x16x32_bf16 v[96:99], v[164:167], v[208:211], v[96:99]
	v_mfma_f32_16x16x32_bf16 v[84:87], v[156:159], v[216:219], v[84:87]
	v_mfma_f32_16x16x32_bf16 v[80:83], v[164:167], v[216:219], v[80:83]
	s_setprio 0
	s_setprio 1
	v_mfma_f32_16x16x32_bf16 v[108:111], v[168:171], v[188:191], 0
	v_mfma_f32_16x16x32_bf16 v[104:107], v[180:183], v[188:191], 0
	v_mfma_f32_16x16x32_bf16 v[92:95], v[168:171], v[196:199], 0
	v_mfma_f32_16x16x32_bf16 v[88:91], v[180:183], v[196:199], 0
	v_mfma_f32_16x16x32_bf16 v[76:79], v[168:171], v[204:207], 0
	v_mfma_f32_16x16x32_bf16 v[72:75], v[180:183], v[204:207], 0
	v_mfma_f32_16x16x32_bf16 v[68:71], v[168:171], v[212:215], 0
	v_mfma_f32_16x16x32_bf16 v[64:67], v[180:183], v[212:215], 0
	v_mfma_f32_16x16x32_bf16 v[108:111], v[172:175], v[192:195], v[108:111]
	v_mfma_f32_16x16x32_bf16 v[104:107], v[184:187], v[192:195], v[104:107]
	v_mfma_f32_16x16x32_bf16 v[92:95], v[172:175], v[200:203], v[92:95]
	v_mfma_f32_16x16x32_bf16 v[88:91], v[184:187], v[200:203], v[88:91]
	v_mfma_f32_16x16x32_bf16 v[76:79], v[172:175], v[208:211], v[76:79]
	v_mfma_f32_16x16x32_bf16 v[72:75], v[184:187], v[208:211], v[72:75]
	v_mfma_f32_16x16x32_bf16 v[68:71], v[172:175], v[216:219], v[68:71]
	v_mfma_f32_16x16x32_bf16 v[64:67], v[184:187], v[216:219], v[64:67]
	s_setprio 0
	s_barrier
; #define PG8_STAGE(bufoff, gbase, voff) do { _Pragma("unroll") for (int _i = 0; _i < 2; ++_i) \
;         __builtin_amdgcn_global_load_lds((const unsigned*)((const char*)(gbase) + (voff)[_i]), (LAS unsigned*)(lds + (bufoff) + ldsw + _i * 8192), 16, 0, 0); } while (0)
; #define PG8_LDA(dst, b, h) do { _Pragma("unroll") for (int m = 0; m < 4; ++m) _Pragma("unroll") for (int k = 0; k < 2; ++k) dst[m][k] = *(const LAS bf16x8*)(lds + PG8_SA(b, h) + aoff + m * 2048 + k * 1024); } while (0)
; #define PG8_MMA(ai, bj, At, Bt) do { __builtin_amdgcn_s_setprio(1); _Pragma("unroll") for (int m = 0; m < 4; ++m) _Pragma("unroll") for (int n = 0; n < 2; ++n) _Pragma("unroll") for (int k = 0; k < 2; ++k) \
;         acc[ai][bj][m][n] = __builtin_amdgcn_mfma_f32_16x16x32_bf16(Bt[n][k], At[m][k], acc[ai][bj][m][n], 0, 0, 0); __builtin_amdgcn_s_setprio(0); } while (0)
; #define PG8_WAIT_V(n) asm volatile("s_waitcnt vmcnt(" #n ")" ::: "memory")
; #define PG8_WAIT_L(n) asm volatile("s_waitcnt lgkmcnt(" #n ")" ::: "memory")
; #define PG8_BAR __builtin_amdgcn_s_barrier()
; #define PG8_SCHED __builtin_amdgcn_sched_barrier(0)
; template <class Epi, class Sched, bool ALIGN_EPI>
; __device__ __forceinline__ void gemm_phase(LAS unsigned char* lds, const int wid, const int lda_, const int ldb_, const int K_, const Sched& S, const Epi& E) {
;     ...
;             PG8_LDA(At, 0, 1); PG8_STAGE(PG8_SB(0, 0), b2, voffB); PG8_STAGE(PG8_SB(0, 1), b2 + hstepB, voffB); PG8_STAGE(PG8_SA(0, 0), a2, voffA);
;             PG8_WAIT_V(8); PG8_WAIT_L(0); PG8_BAR; PG8_MMA(1, 0, At, B0); PG8_MMA(1, 1, At, B1); PG8_BAR; PG8_SCHED;
	s_mov_b32 m0, s87
	v_lshl_add_u64 v[220:221], s[50:51], 0, v[176:177]
	ds_read_b128 v[188:191], v139 offset:16384
	ds_read_b128 v[192:195], v139 offset:17408
	ds_read_b128 v[196:199], v139 offset:18432
	ds_read_b128 v[200:203], v139 offset:19456
	ds_read_b128 v[204:207], v139 offset:20480
	ds_read_b128 v[208:211], v139 offset:21504
	ds_read_b128 v[212:215], v139 offset:22528
	ds_read_b128 v[216:219], v139 offset:23552
	global_load_lds_dwordx4 v[220:221], off
	v_lshl_add_u64 v[222:223], s[50:51], 0, v[128:129]
	s_mov_b32 m0, s80
	v_lshl_add_u64 v[224:225], s[96:97], 0, v[176:177]
	global_load_lds_dwordx4 v[222:223], off
	s_mov_b32 m0, s86
	v_lshl_add_u64 v[226:227], s[96:97], 0, v[128:129]
	global_load_lds_dwordx4 v[224:225], off
	s_mov_b32 m0, s81
	v_lshl_add_u64 v[228:229], s[94:95], 0, v[132:133]
	global_load_lds_dwordx4 v[226:227], off
	s_mov_b32 m0, s16
	v_lshl_add_u64 v[230:231], s[94:95], 0, v[130:131]
	global_load_lds_dwordx4 v[228:229], off
	s_mov_b32 m0, s6
	s_nop 0
	global_load_lds_dwordx4 v[230:231], off
	s_waitcnt vmcnt(24)
	s_waitcnt lgkmcnt(0)
	s_barrier
	s_setprio 1
	s_waitcnt lgkmcnt(0)
	v_mfma_f32_16x16x32_bf16 v[60:63], v[152:155], v[188:191], 0
	v_mfma_f32_16x16x32_bf16 v[56:59], v[160:163], v[188:191], 0
	v_mfma_f32_16x16x32_bf16 v[52:55], v[152:155], v[196:199], 0
	v_mfma_f32_16x16x32_bf16 v[48:51], v[160:163], v[196:199], 0
	v_mfma_f32_16x16x32_bf16 v[36:39], v[152:155], v[204:207], 0
	v_mfma_f32_16x16x32_bf16 v[32:35], v[160:163], v[204:207], 0
	v_mfma_f32_16x16x32_bf16 v[20:23], v[152:155], v[212:215], 0
	v_mfma_f32_16x16x32_bf16 v[16:19], v[160:163], v[212:215], 0
	v_mfma_f32_16x16x32_bf16 v[60:63], v[156:159], v[192:195], v[60:63]
	v_mfma_f32_16x16x32_bf16 v[56:59], v[164:167], v[192:195], v[56:59]
	v_mfma_f32_16x16x32_bf16 v[52:55], v[156:159], v[200:203], v[52:55]
	v_mfma_f32_16x16x32_bf16 v[48:51], v[164:167], v[200:203], v[48:51]
	v_mfma_f32_16x16x32_bf16 v[36:39], v[156:159], v[208:211], v[36:39]
	v_mfma_f32_16x16x32_bf16 v[32:35], v[164:167], v[208:211], v[32:35]
	v_mfma_f32_16x16x32_bf16 v[20:23], v[156:159], v[216:219], v[20:23]
	v_mfma_f32_16x16x32_bf16 v[16:19], v[164:167], v[216:219], v[16:19]
	s_setprio 0
	s_setprio 1
	v_mfma_f32_16x16x32_bf16 v[44:47], v[168:171], v[188:191], 0
	v_mfma_f32_16x16x32_bf16 v[40:43], v[180:183], v[188:191], 0
	v_mfma_f32_16x16x32_bf16 v[28:31], v[168:171], v[196:199], 0
	v_mfma_f32_16x16x32_bf16 v[24:27], v[180:183], v[196:199], 0
	v_mfma_f32_16x16x32_bf16 v[12:15], v[168:171], v[204:207], 0
	v_mfma_f32_16x16x32_bf16 v[8:11], v[180:183], v[204:207], 0
	v_mfma_f32_16x16x32_bf16 v[4:7], v[168:171], v[212:215], 0
	v_mfma_f32_16x16x32_bf16 v[0:3], v[180:183], v[212:215], 0
	v_mfma_f32_16x16x32_bf16 v[44:47], v[172:175], v[192:195], v[44:47]
	v_mfma_f32_16x16x32_bf16 v[40:43], v[184:187], v[192:195], v[40:43]
	v_mfma_f32_16x16x32_bf16 v[28:31], v[172:175], v[200:203], v[28:31]
	v_mfma_f32_16x16x32_bf16 v[24:27], v[184:187], v[200:203], v[24:27]
	v_mfma_f32_16x16x32_bf16 v[12:15], v[172:175], v[208:211], v[12:15]
	v_mfma_f32_16x16x32_bf16 v[8:11], v[184:187], v[208:211], v[8:11]
	v_mfma_f32_16x16x32_bf16 v[4:7], v[172:175], v[216:219], v[4:7]
	v_mfma_f32_16x16x32_bf16 v[0:3], v[184:187], v[216:219], v[0:3]
	s_setprio 0
	s_barrier
	s_branch .Lgemm_join_697

; #define PG8_STAGE(bufoff, gbase, voff) do { _Pragma("unroll") for (int _i = 0; _i < 2; ++_i) \
;         __builtin_amdgcn_global_load_lds((const unsigned*)((const char*)(gbase) + (voff)[_i]), (LAS unsigned*)(lds + (bufoff) + ldsw + _i * 8192), 16, 0, 0); } while (0)
; #define PG8_LDA(dst, b, h) do { _Pragma("unroll") for (int m = 0; m < 4; ++m) _Pragma("unroll") for (int k = 0; k < 2; ++k) dst[m][k] = *(const LAS bf16x8*)(lds + PG8_SA(b, h) + aoff + m * 2048 + k * 1024); } while (0)
; #define PG8_LDB(dst, b, h) do { _Pragma("unroll") for (int n = 0; n < 2; ++n) _Pragma("unroll") for (int k = 0; k < 2; ++k) dst[n][k] = *(const LAS bf16x8*)(lds + PG8_SB(b, h) + boff + n * 2048 + k * 1024); } while (0)
; #define PG8_WAIT_V(n) asm volatile("s_waitcnt vmcnt(" #n ")" ::: "memory")
; template <class Epi, class Sched, bool ALIGN_EPI>
; __device__ __forceinline__ void gemm_phase(LAS unsigned char* lds, const int wid, const int lda_, const int ldb_, const int K_, const Sched& S, const Epi& E) {
;     ...
;     PG8_STAGE(PG8_SB(0, 0), cB, voffB); PG8_STAGE(PG8_SB(0, 1), cB + hstepB, voffB); PG8_STAGE(PG8_SA(0, 0), cA, voffA); PG8_STAGE(PG8_SA(0, 1), cA + hstepA, voffA);
;     if (wr == 1) PG8_BAR;
;     PG8_WAIT_V(2); PG8_BAR;
;     PG8_STAGE(PG8_SB(1, 0), cB + kstep, voffB); PG8_STAGE(PG8_SA(1, 0), cA + kstep, voffA); PG8_STAGE(PG8_SB(1, 1), cB + hstepB + kstep, voffB);
;     PG8_WAIT_V(6); PG8_BAR;
;     for (;;) {
;         const bool has_next = S.next(ui + 1, nxt);
;         const int nt = S.nt(cur);
;         const char* nA = has_next ? S.a(nxt) : cA; const char* nB = has_next ? S.b(nxt) : cB;
; #pragma unroll 1
;         for (int t = 0; t < nt; t += 2) {
;             const bool last = (t == nt - 2);
;             const char* a1 = cA + (size_t)(t + 1) * kstep;
;             const char* a2 = last ? nA : cA + (size_t)(t + 2) * kstep; const char* b2 = last ? nB : cB + (size_t)(t + 2) * kstep;
;             const char* a3 = a2 + kstep; const char* b3 = b2 + kstep;
;             PG8_LDB(B0, 0, 0); PG8_LDB(B1, 0, 1); PG8_SCHED; PG8_LDA(At, 0, 0); PG8_STAGE(PG8_SA(1, 1), a1 + hstepA, voffA);
;             PG8_WAIT_V(8); PG8_WAIT_L(0); PG8_BAR; PG8_MMA(0, 0, At, B0); PG8_MMA(0, 1, At, B1); PG8_BAR; PG8_SCHED;
;     __device__ __forceinline__ const char* a(const pg8::Unit& u) const { return (const char*)ws + (u.pm < 64 ? WS_W2 : WS_W2C); }
.LBB0_882:
	s_and_b64 s[4:5], s[4:5], exec
	s_cselect_b32 s4, s27, 0x380000
	s_add_u32 s44, s66, s4
	s_addc_u32 s45, s67, 0
	s_and_b64 s[4:5], s[50:51], exec
	s_cselect_b32 s4, s45, s47
	s_cselect_b32 s5, s44, s46
	s_add_u32 s42, s46, 0x80
	s_addc_u32 s43, s47, 0
	s_add_u32 s31, s48, 0x100
	v_lshl_add_u64 v[156:157], s[42:43], 0, v[152:153]
	v_lshl_add_u64 v[158:159], s[42:43], 0, v[154:155]
	s_addc_u32 s35, s49, 0
	s_mov_b32 s73, -2
	s_mov_b64 s[48:49], 0
	s_add_u32 s17, s46, s48
	s_addc_u32 s27, s47, s49
	s_add_u32 s17, s17, 0x100
	s_addc_u32 s27, s27, 0
	s_add_u32 s42, s31, s48
	s_addc_u32 s43, s35, s49
	s_add_i32 s74, 0, 0x10000
	s_cmpk_eq_i32 s48, 0x300
	s_cselect_b32 s51, s4, s27
	s_cselect_b32 s50, s5, s17
	v_add_u32_e32 v141, s74, v135
	s_cselect_b32 s43, s39, s43
	s_cselect_b32 s42, s38, s42
	s_add_i32 s17, 0, 0x14000
	ds_read_b128 v[160:163], v141
	ds_read_b128 v[164:167], v141 offset:1024
	ds_read_b128 v[168:171], v141 offset:2048
	ds_read_b128 v[172:175], v141 offset:3072
	v_add_u32_e32 v141, s17, v135
	ds_read_b128 v[180:183], v141
	ds_read_b128 v[184:187], v141 offset:1024
	ds_read_b128 v[188:191], v141 offset:2048
	ds_read_b128 v[192:195], v141 offset:3072
	v_lshl_add_u64 v[228:229], v[158:159], 0, s[48:49]
	s_add_i32 m0, s16, 0xc000
	ds_read_b128 v[196:199], v139
	ds_read_b128 v[200:203], v139 offset:1024
	ds_read_b128 v[204:207], v139 offset:2048
	ds_read_b128 v[208:211], v139 offset:3072
	ds_read_b128 v[212:215], v139 offset:4096
	ds_read_b128 v[216:219], v139 offset:5120
	ds_read_b128 v[220:223], v139 offset:6144
	ds_read_b128 v[224:227], v139 offset:7168
	global_load_lds_dwordx4 v[228:229], off
	v_lshl_add_u64 v[228:229], v[156:157], 0, s[48:49]
	s_add_i32 m0, s16, 0xe000
	s_nop 0
	global_load_lds_dwordx4 v[228:229], off
	s_waitcnt vmcnt(24)
	s_waitcnt lgkmcnt(0)
	s_barrier
	s_setprio 1
	s_waitcnt lgkmcnt(0)
	v_mfma_f32_16x16x32_bf16 v[124:127], v[160:163], v[196:199], 0
	v_mfma_f32_16x16x32_bf16 v[120:123], v[168:171], v[196:199], 0
	v_mfma_f32_16x16x32_bf16 v[116:119], v[160:163], v[204:207], 0
	v_mfma_f32_16x16x32_bf16 v[112:115], v[168:171], v[204:207], 0
	v_mfma_f32_16x16x32_bf16 v[100:103], v[160:163], v[212:215], 0
	v_mfma_f32_16x16x32_bf16 v[96:99], v[168:171], v[212:215], 0
	v_mfma_f32_16x16x32_bf16 v[84:87], v[160:163], v[220:223], 0
	v_mfma_f32_16x16x32_bf16 v[80:83], v[168:171], v[220:223], 0
	v_mfma_f32_16x16x32_bf16 v[124:127], v[164:167], v[200:203], v[124:127]
	v_mfma_f32_16x16x32_bf16 v[120:123], v[172:175], v[200:203], v[120:123]
	v_mfma_f32_16x16x32_bf16 v[116:119], v[164:167], v[208:211], v[116:119]
	v_mfma_f32_16x16x32_bf16 v[112:115], v[172:175], v[208:211], v[112:115]
	v_mfma_f32_16x16x32_bf16 v[100:103], v[164:167], v[216:219], v[100:103]
	v_mfma_f32_16x16x32_bf16 v[96:99], v[172:175], v[216:219], v[96:99]
	v_mfma_f32_16x16x32_bf16 v[84:87], v[164:167], v[224:227], v[84:87]
	v_mfma_f32_16x16x32_bf16 v[80:83], v[172:175], v[224:227], v[80:83]
	s_setprio 0
	s_setprio 1
	v_mfma_f32_16x16x32_bf16 v[108:111], v[180:183], v[196:199], 0
	v_mfma_f32_16x16x32_bf16 v[104:107], v[188:191], v[196:199], 0
	v_mfma_f32_16x16x32_bf16 v[92:95], v[180:183], v[204:207], 0
	v_mfma_f32_16x16x32_bf16 v[88:91], v[188:191], v[204:207], 0
	v_mfma_f32_16x16x32_bf16 v[76:79], v[180:183], v[212:215], 0
	v_mfma_f32_16x16x32_bf16 v[72:75], v[188:191], v[212:215], 0
	v_mfma_f32_16x16x32_bf16 v[68:71], v[180:183], v[220:223], 0
	v_mfma_f32_16x16x32_bf16 v[64:67], v[188:191], v[220:223], 0
	v_mfma_f32_16x16x32_bf16 v[108:111], v[184:187], v[200:203], v[108:111]
	v_mfma_f32_16x16x32_bf16 v[104:107], v[192:195], v[200:203], v[104:107]
	v_mfma_f32_16x16x32_bf16 v[92:95], v[184:187], v[208:211], v[92:95]
	v_mfma_f32_16x16x32_bf16 v[88:91], v[192:195], v[208:211], v[88:91]
	v_mfma_f32_16x16x32_bf16 v[76:79], v[184:187], v[216:219], v[76:79]
	v_mfma_f32_16x16x32_bf16 v[72:75], v[192:195], v[216:219], v[72:75]
	v_mfma_f32_16x16x32_bf16 v[68:71], v[184:187], v[224:227], v[68:71]
	v_mfma_f32_16x16x32_bf16 v[64:67], v[192:195], v[224:227], v[64:67]
	s_setprio 0
	s_barrier
; #define PG8_STAGE(bufoff, gbase, voff) do { _Pragma("unroll") for (int _i = 0; _i < 2; ++_i) \
;         __builtin_amdgcn_global_load_lds((const unsigned*)((const char*)(gbase) + (voff)[_i]), (LAS unsigned*)(lds + (bufoff) + ldsw + _i * 8192), 16, 0, 0); } while (0)
; #define PG8_LDA(dst, b, h) do { _Pragma("unroll") for (int m = 0; m < 4; ++m) _Pragma("unroll") for (int k = 0; k < 2; ++k) dst[m][k] = *(const LAS bf16x8*)(lds + PG8_SA(b, h) + aoff + m * 2048 + k * 1024); } while (0)
; #define PG8_MMA(ai, bj, At, Bt) do { __builtin_amdgcn_s_setprio(1); _Pragma("unroll") for (int m = 0; m < 4; ++m) _Pragma("unroll") for (int n = 0; n < 2; ++n) _Pragma("unroll") for (int k = 0; k < 2; ++k) \
;         acc[ai][bj][m][n] = __builtin_amdgcn_mfma_f32_16x16x32_bf16(Bt[n][k], At[m][k], acc[ai][bj][m][n], 0, 0, 0); __builtin_amdgcn_s_setprio(0); } while (0)
; #define PG8_WAIT_V(n) asm volatile("s_waitcnt vmcnt(" #n ")" ::: "memory")
; #define PG8_WAIT_L(n) asm volatile("s_waitcnt lgkmcnt(" #n ")" ::: "memory")
; #define PG8_BAR __builtin_amdgcn_s_barrier()
; #define PG8_SCHED __builtin_amdgcn_sched_barrier(0)
; template <class Epi, class Sched, bool ALIGN_EPI>
; __device__ __forceinline__ void gemm_phase(LAS unsigned char* lds, const int wid, const int lda_, const int ldb_, const int K_, const Sched& S, const Epi& E) {
;     ...
;             PG8_LDA(At, 0, 1); PG8_STAGE(PG8_SB(0, 0), b2, voffB); PG8_STAGE(PG8_SB(0, 1), b2 + hstepB, voffB); PG8_STAGE(PG8_SA(0, 0), a2, voffA);
;             PG8_WAIT_V(8); PG8_WAIT_L(0); PG8_BAR; PG8_MMA(1, 0, At, B0); PG8_MMA(1, 1, At, B1); PG8_BAR; PG8_SCHED;
	s_add_i32 s27, s74, s3
	v_lshl_add_u64 v[228:229], s[42:43], 0, v[176:177]
	s_mov_b32 m0, s27
	ds_read_b128 v[196:199], v139 offset:16384
	ds_read_b128 v[200:203], v139 offset:17408
	ds_read_b128 v[204:207], v139 offset:18432
	ds_read_b128 v[208:211], v139 offset:19456
	ds_read_b128 v[212:215], v139 offset:20480
	ds_read_b128 v[216:219], v139 offset:21504
	ds_read_b128 v[220:223], v139 offset:22528
	ds_read_b128 v[224:227], v139 offset:23552
	global_load_lds_dwordx4 v[228:229], off
	s_add_i32 m0, s27, 0x2000
	v_lshl_add_u64 v[230:231], s[42:43], 0, v[132:133]
	s_add_u32 s42, s42, s10
	s_addc_u32 s43, s43, s11
	s_add_i32 s17, s17, s3
	global_load_lds_dwordx4 v[230:231], off
	v_lshl_add_u64 v[232:233], s[42:43], 0, v[176:177]
	s_mov_b32 m0, s17
	v_lshl_add_u64 v[234:235], s[42:43], 0, v[132:133]
	global_load_lds_dwordx4 v[232:233], off
	s_add_i32 m0, s17, 0x2000
	v_lshl_add_u64 v[236:237], s[50:51], 0, v[128:129]
	global_load_lds_dwordx4 v[234:235], off
	s_mov_b32 m0, s16
	v_lshl_add_u64 v[246:247], s[50:51], 0, v[130:131]
	global_load_lds_dwordx4 v[236:237], off
	s_mov_b32 m0, s6
	s_nop 0
	global_load_lds_dwordx4 v[246:247], off
	s_waitcnt vmcnt(24)
	s_waitcnt lgkmcnt(0)
	s_barrier
	s_setprio 1
	s_waitcnt lgkmcnt(0)
	v_mfma_f32_16x16x32_bf16 v[60:63], v[160:163], v[196:199], 0
	v_mfma_f32_16x16x32_bf16 v[56:59], v[168:171], v[196:199], 0
	v_mfma_f32_16x16x32_bf16 v[52:55], v[160:163], v[204:207], 0
	v_mfma_f32_16x16x32_bf16 v[48:51], v[168:171], v[204:207], 0
	v_mfma_f32_16x16x32_bf16 v[36:39], v[160:163], v[212:215], 0
	v_mfma_f32_16x16x32_bf16 v[32:35], v[168:171], v[212:215], 0
	v_mfma_f32_16x16x32_bf16 v[20:23], v[160:163], v[220:223], 0
	v_mfma_f32_16x16x32_bf16 v[16:19], v[168:171], v[220:223], 0
	v_mfma_f32_16x16x32_bf16 v[60:63], v[164:167], v[200:203], v[60:63]
	v_mfma_f32_16x16x32_bf16 v[56:59], v[172:175], v[200:203], v[56:59]
	v_mfma_f32_16x16x32_bf16 v[52:55], v[164:167], v[208:211], v[52:55]
	v_mfma_f32_16x16x32_bf16 v[48:51], v[172:175], v[208:211], v[48:51]
	v_mfma_f32_16x16x32_bf16 v[36:39], v[164:167], v[216:219], v[36:39]
	v_mfma_f32_16x16x32_bf16 v[32:35], v[172:175], v[216:219], v[32:35]
	v_mfma_f32_16x16x32_bf16 v[20:23], v[164:167], v[224:227], v[20:23]
	v_mfma_f32_16x16x32_bf16 v[16:19], v[172:175], v[224:227], v[16:19]
	s_setprio 0
	s_setprio 1
	v_mfma_f32_16x16x32_bf16 v[44:47], v[180:183], v[196:199], 0
	v_mfma_f32_16x16x32_bf16 v[40:43], v[188:191], v[196:199], 0
	v_mfma_f32_16x16x32_bf16 v[28:31], v[180:183], v[204:207], 0
	v_mfma_f32_16x16x32_bf16 v[24:27], v[188:191], v[204:207], 0
	v_mfma_f32_16x16x32_bf16 v[12:15], v[180:183], v[212:215], 0
	v_mfma_f32_16x16x32_bf16 v[8:11], v[188:191], v[212:215], 0
	v_mfma_f32_16x16x32_bf16 v[4:7], v[180:183], v[220:223], 0
	v_mfma_f32_16x16x32_bf16 v[0:3], v[188:191], v[220:223], 0
	v_mfma_f32_16x16x32_bf16 v[44:47], v[184:187], v[200:203], v[44:47]
	v_mfma_f32_16x16x32_bf16 v[40:43], v[192:195], v[200:203], v[40:43]
	v_mfma_f32_16x16x32_bf16 v[28:31], v[184:187], v[208:211], v[28:31]
	v_mfma_f32_16x16x32_bf16 v[24:27], v[192:195], v[208:211], v[24:27]
	v_mfma_f32_16x16x32_bf16 v[12:15], v[184:187], v[216:219], v[12:15]
	v_mfma_f32_16x16x32_bf16 v[8:11], v[192:195], v[216:219], v[8:11]
	v_mfma_f32_16x16x32_bf16 v[4:7], v[184:187], v[224:227], v[4:7]
	v_mfma_f32_16x16x32_bf16 v[0:3], v[192:195], v[224:227], v[0:3]
	s_setprio 0
	s_barrier
	s_branch .Lgemm_join_883

; #define PG8_STAGE(bufoff, gbase, voff) do { _Pragma("unroll") for (int _i = 0; _i < 2; ++_i) \
;         __builtin_amdgcn_global_load_lds((const unsigned*)((const char*)(gbase) + (voff)[_i]), (LAS unsigned*)(lds + (bufoff) + ldsw + _i * 8192), 16, 0, 0); } while (0)
; #define PG8_LDA(dst, b, h) do { _Pragma("unroll") for (int m = 0; m < 4; ++m) _Pragma("unroll") for (int k = 0; k < 2; ++k) dst[m][k] = *(const LAS bf16x8*)(lds + PG8_SA(b, h) + aoff + m * 2048 + k * 1024); } while (0)
; #define PG8_LDB(dst, b, h) do { _Pragma("unroll") for (int n = 0; n < 2; ++n) _Pragma("unroll") for (int k = 0; k < 2; ++k) dst[n][k] = *(const LAS bf16x8*)(lds + PG8_SB(b, h) + boff + n * 2048 + k * 1024); } while (0)
; #define PG8_WAIT_V(n) asm volatile("s_waitcnt vmcnt(" #n ")" ::: "memory")
; #define PG8_WAIT_L(n) asm volatile("s_waitcnt lgkmcnt(" #n ")" ::: "memory")
; #define PG8_BAR __builtin_amdgcn_s_barrier()
; template <class Epi, class Sched, bool ALIGN_EPI>
; __device__ __forceinline__ void gemm_phase(LAS unsigned char* lds, const int wid, const int lda_, const int ldb_, const int K_, const Sched& S, const Epi& E) {
;     ...
;     PG8_STAGE(PG8_SB(0, 0), cB, voffB); PG8_STAGE(PG8_SB(0, 1), cB + hstepB, voffB); PG8_STAGE(PG8_SA(0, 0), cA, voffA); PG8_STAGE(PG8_SA(0, 1), cA + hstepA, voffA);
;     if (wr == 1) PG8_BAR;
;     PG8_WAIT_V(2); PG8_BAR;
;     PG8_STAGE(PG8_SB(1, 0), cB + kstep, voffB); PG8_STAGE(PG8_SA(1, 0), cA + kstep, voffA); PG8_STAGE(PG8_SB(1, 1), cB + hstepB + kstep, voffB);
;     PG8_WAIT_V(6); PG8_BAR;
;     for (;;) {
;         const bool has_next = S.next(ui + 1, nxt);
;         const int nt = S.nt(cur);
;         const char* nA = has_next ? S.a(nxt) : cA; const char* nB = has_next ? S.b(nxt) : cB;
; #pragma unroll 1
;         for (int t = 0; t < nt; t += 2) {
;             const bool last = (t == nt - 2);
;             const char* a1 = cA + (size_t)(t + 1) * kstep;
;             const char* a2 = last ? nA : cA + (size_t)(t + 2) * kstep; const char* b2 = last ? nB : cB + (size_t)(t + 2) * kstep;
;             const char* a3 = a2 + kstep; const char* b3 = b2 + kstep;
;             PG8_LDB(B0, 0, 0); PG8_LDB(B1, 0, 1); PG8_SCHED; PG8_LDA(At, 0, 0); PG8_STAGE(PG8_SA(1, 1), a1 + hstepA, voffA);
;             PG8_WAIT_V(8); PG8_WAIT_L(0); PG8_BAR; PG8_MMA(0, 0, At, B0); PG8_MMA(0, 1, At, B1); PG8_BAR; PG8_SCHED;
.LBB0_961:
	s_xor_b64 s[36:37], s[4:5], -1
	s_cmp_gt_i32 s48, -1
	s_cselect_b64 s[50:51], -1, 0
	s_cmp_lt_i32 s48, 0
	s_cselect_b32 s45, 32, 8
	s_max_i32 s17, s75, 0
	s_ashr_i32 s35, s34, 31
	s_lshl_b32 s17, s17, 10
	s_lshl_b64 s[38:39], s[34:35], 20
	v_readlane_b32 s27, v254, 19
	s_add_u32 s27, s27, s38
	v_readlane_b32 s31, v254, 20
	s_addc_u32 s31, s31, s39
	s_add_u32 s38, s27, s17
	s_addc_u32 s39, s31, 0
	s_and_b64 s[40:41], s[4:5], exec
	s_cselect_b32 s35, s39, s95
	s_cselect_b32 s47, s38, s94
	s_ashr_i32 s31, s30, 31
	s_lshl_b64 s[40:41], s[30:31], 20
	s_add_u32 s27, s6, s40
	s_addc_u32 s31, s7, s41
	s_add_u32 s40, s27, s17
	s_addc_u32 s41, s31, 0
	s_and_b64 s[4:5], s[4:5], exec
	s_cselect_b32 s4, s41, s97
	s_cselect_b32 s5, s40, s96
	s_add_i32 s31, s45, -2
	s_add_u32 s94, s94, 0x80
	s_addc_u32 s95, s95, 0
	s_add_u32 s49, s96, 0x100
	s_mov_b32 s77, 0
	s_addc_u32 s76, s97, 0
	s_add_i32 s78, s77, 2
	s_add_u32 s17, s94, 0x80
	s_addc_u32 s27, s95, 0
	s_add_i32 s79, 0, 0x10000
	s_cmp_eq_u32 s31, s77
	s_cselect_b32 s97, s35, s27
	s_cselect_b32 s96, s47, s17
	v_add_u32_e32 v141, s79, v135
	s_cselect_b32 s43, s4, s76
	s_cselect_b32 s42, s5, s49
	s_add_i32 s17, 0, 0x14000
	ds_read_b128 v[156:159], v141
	ds_read_b128 v[160:163], v141 offset:1024
	ds_read_b128 v[164:167], v141 offset:2048
	ds_read_b128 v[168:171], v141 offset:3072
	v_add_u32_e32 v141, s17, v135
	ds_read_b128 v[172:175], v141
	ds_read_b128 v[180:183], v141 offset:1024
	ds_read_b128 v[184:187], v141 offset:2048
	ds_read_b128 v[188:191], v141 offset:3072
	v_lshl_add_u64 v[224:225], s[94:95], 0, v[152:153]
	s_add_i32 m0, s16, 0xc000
	ds_read_b128 v[192:195], v139
	ds_read_b128 v[196:199], v139 offset:1024
	ds_read_b128 v[200:203], v139 offset:2048
	ds_read_b128 v[204:207], v139 offset:3072
	ds_read_b128 v[208:211], v139 offset:4096
	ds_read_b128 v[212:215], v139 offset:5120
	ds_read_b128 v[216:219], v139 offset:6144
	ds_read_b128 v[220:223], v139 offset:7168
	global_load_lds_dwordx4 v[224:225], off
	v_lshl_add_u64 v[224:225], s[94:95], 0, v[154:155]
	s_add_i32 m0, s16, 0xe000
	s_nop 0
	global_load_lds_dwordx4 v[224:225], off
	s_waitcnt vmcnt(24)
	s_waitcnt lgkmcnt(0)
	s_barrier
	s_setprio 1
	s_waitcnt lgkmcnt(0)
	v_mfma_f32_16x16x32_bf16 v[124:127], v[156:159], v[192:195], 0
	v_mfma_f32_16x16x32_bf16 v[120:123], v[164:167], v[192:195], 0
	v_mfma_f32_16x16x32_bf16 v[116:119], v[156:159], v[200:203], 0
	v_mfma_f32_16x16x32_bf16 v[112:115], v[164:167], v[200:203], 0
	v_mfma_f32_16x16x32_bf16 v[100:103], v[156:159], v[208:211], 0
	v_mfma_f32_16x16x32_bf16 v[96:99], v[164:167], v[208:211], 0
	v_mfma_f32_16x16x32_bf16 v[84:87], v[156:159], v[216:219], 0
	v_mfma_f32_16x16x32_bf16 v[80:83], v[164:167], v[216:219], 0
	v_mfma_f32_16x16x32_bf16 v[124:127], v[160:163], v[196:199], v[124:127]
	v_mfma_f32_16x16x32_bf16 v[120:123], v[168:171], v[196:199], v[120:123]
	v_mfma_f32_16x16x32_bf16 v[116:119], v[160:163], v[204:207], v[116:119]
	v_mfma_f32_16x16x32_bf16 v[112:115], v[168:171], v[204:207], v[112:115]
	v_mfma_f32_16x16x32_bf16 v[100:103], v[160:163], v[212:215], v[100:103]
	v_mfma_f32_16x16x32_bf16 v[96:99], v[168:171], v[212:215], v[96:99]
	v_mfma_f32_16x16x32_bf16 v[84:87], v[160:163], v[220:223], v[84:87]
	v_mfma_f32_16x16x32_bf16 v[80:83], v[168:171], v[220:223], v[80:83]
	s_setprio 0
	s_setprio 1
	v_mfma_f32_16x16x32_bf16 v[108:111], v[172:175], v[192:195], 0
	v_mfma_f32_16x16x32_bf16 v[104:107], v[184:187], v[192:195], 0
	v_mfma_f32_16x16x32_bf16 v[92:95], v[172:175], v[200:203], 0
	v_mfma_f32_16x16x32_bf16 v[88:91], v[184:187], v[200:203], 0
	v_mfma_f32_16x16x32_bf16 v[76:79], v[172:175], v[208:211], 0
	v_mfma_f32_16x16x32_bf16 v[72:75], v[184:187], v[208:211], 0
	v_mfma_f32_16x16x32_bf16 v[68:71], v[172:175], v[216:219], 0
	v_mfma_f32_16x16x32_bf16 v[64:67], v[184:187], v[216:219], 0
	v_mfma_f32_16x16x32_bf16 v[108:111], v[180:183], v[196:199], v[108:111]
	v_mfma_f32_16x16x32_bf16 v[104:107], v[188:191], v[196:199], v[104:107]
	v_mfma_f32_16x16x32_bf16 v[92:95], v[180:183], v[204:207], v[92:95]
	v_mfma_f32_16x16x32_bf16 v[88:91], v[188:191], v[204:207], v[88:91]
	v_mfma_f32_16x16x32_bf16 v[76:79], v[180:183], v[212:215], v[76:79]
	v_mfma_f32_16x16x32_bf16 v[72:75], v[188:191], v[212:215], v[72:75]
	v_mfma_f32_16x16x32_bf16 v[68:71], v[180:183], v[220:223], v[68:71]
	v_mfma_f32_16x16x32_bf16 v[64:67], v[188:191], v[220:223], v[64:67]
	s_setprio 0
	s_barrier
; #define PG8_STAGE(bufoff, gbase, voff) do { _Pragma("unroll") for (int _i = 0; _i < 2; ++_i) \
;         __builtin_amdgcn_global_load_lds((const unsigned*)((const char*)(gbase) + (voff)[_i]), (LAS unsigned*)(lds + (bufoff) + ldsw + _i * 8192), 16, 0, 0); } while (0)
; #define PG8_LDA(dst, b, h) do { _Pragma("unroll") for (int m = 0; m < 4; ++m) _Pragma("unroll") for (int k = 0; k < 2; ++k) dst[m][k] = *(const LAS bf16x8*)(lds + PG8_SA(b, h) + aoff + m * 2048 + k * 1024); } while (0)
; #define PG8_MMA(ai, bj, At, Bt) do { __builtin_amdgcn_s_setprio(1); _Pragma("unroll") for (int m = 0; m < 4; ++m) _Pragma("unroll") for (int n = 0; n < 2; ++n) _Pragma("unroll") for (int k = 0; k < 2; ++k) \
;         acc[ai][bj][m][n] = __builtin_amdgcn_mfma_f32_16x16x32_bf16(Bt[n][k], At[m][k], acc[ai][bj][m][n], 0, 0, 0); __builtin_amdgcn_s_setprio(0); } while (0)
; #define PG8_WAIT_V(n) asm volatile("s_waitcnt vmcnt(" #n ")" ::: "memory")
; #define PG8_WAIT_L(n) asm volatile("s_waitcnt lgkmcnt(" #n ")" ::: "memory")
; #define PG8_BAR __builtin_amdgcn_s_barrier()
; #define PG8_SCHED __builtin_amdgcn_sched_barrier(0)
; template <class Epi, class Sched, bool ALIGN_EPI>
; __device__ __forceinline__ void gemm_phase(LAS unsigned char* lds, const int wid, const int lda_, const int ldb_, const int K_, const Sched& S, const Epi& E) {
;     ...
;             PG8_LDA(At, 0, 1); PG8_STAGE(PG8_SB(0, 0), b2, voffB); PG8_STAGE(PG8_SB(0, 1), b2 + hstepB, voffB); PG8_STAGE(PG8_SA(0, 0), a2, voffA);
;             PG8_WAIT_V(8); PG8_WAIT_L(0); PG8_BAR; PG8_MMA(1, 0, At, B0); PG8_MMA(1, 1, At, B1); PG8_BAR; PG8_SCHED;
	s_add_i32 s27, s79, s3
	v_lshl_add_u64 v[224:225], s[42:43], 0, v[176:177]
	s_mov_b32 m0, s27
	ds_read_b128 v[192:195], v139 offset:16384
	ds_read_b128 v[196:199], v139 offset:17408
	ds_read_b128 v[200:203], v139 offset:18432
	ds_read_b128 v[204:207], v139 offset:19456
	ds_read_b128 v[208:211], v139 offset:20480
	ds_read_b128 v[212:215], v139 offset:21504
	ds_read_b128 v[216:219], v139 offset:22528
	ds_read_b128 v[220:223], v139 offset:23552
	global_load_lds_dwordx4 v[224:225], off
	s_add_i32 m0, s27, 0x2000
	v_lshl_add_u64 v[226:227], s[42:43], 0, v[128:129]
	s_add_u32 s42, s42, s10
	s_addc_u32 s43, s43, s11
	s_add_i32 s17, s17, s3
	global_load_lds_dwordx4 v[226:227], off
	v_lshl_add_u64 v[228:229], s[42:43], 0, v[176:177]
	s_mov_b32 m0, s17
	v_lshl_add_u64 v[230:231], s[42:43], 0, v[128:129]
	global_load_lds_dwordx4 v[228:229], off
	s_add_i32 m0, s17, 0x2000
	v_lshl_add_u64 v[232:233], s[96:97], 0, v[132:133]
	global_load_lds_dwordx4 v[230:231], off
	s_mov_b32 m0, s16
	v_lshl_add_u64 v[234:235], s[96:97], 0, v[130:131]
	global_load_lds_dwordx4 v[232:233], off
	s_mov_b32 m0, s14
	s_nop 0
	global_load_lds_dwordx4 v[234:235], off
	s_waitcnt vmcnt(24)
	s_waitcnt lgkmcnt(0)
	s_barrier
	s_setprio 1
	s_waitcnt lgkmcnt(0)
	v_mfma_f32_16x16x32_bf16 v[60:63], v[156:159], v[192:195], 0
	v_mfma_f32_16x16x32_bf16 v[56:59], v[164:167], v[192:195], 0
	v_mfma_f32_16x16x32_bf16 v[52:55], v[156:159], v[200:203], 0
	v_mfma_f32_16x16x32_bf16 v[48:51], v[164:167], v[200:203], 0
	v_mfma_f32_16x16x32_bf16 v[36:39], v[156:159], v[208:211], 0
	v_mfma_f32_16x16x32_bf16 v[32:35], v[164:167], v[208:211], 0
	v_mfma_f32_16x16x32_bf16 v[20:23], v[156:159], v[216:219], 0
	v_mfma_f32_16x16x32_bf16 v[16:19], v[164:167], v[216:219], 0
	v_mfma_f32_16x16x32_bf16 v[60:63], v[160:163], v[196:199], v[60:63]
	v_mfma_f32_16x16x32_bf16 v[56:59], v[168:171], v[196:199], v[56:59]
	v_mfma_f32_16x16x32_bf16 v[52:55], v[160:163], v[204:207], v[52:55]
	v_mfma_f32_16x16x32_bf16 v[48:51], v[168:171], v[204:207], v[48:51]
	v_mfma_f32_16x16x32_bf16 v[36:39], v[160:163], v[212:215], v[36:39]
	v_mfma_f32_16x16x32_bf16 v[32:35], v[168:171], v[212:215], v[32:35]
	v_mfma_f32_16x16x32_bf16 v[20:23], v[160:163], v[220:223], v[20:23]
	v_mfma_f32_16x16x32_bf16 v[16:19], v[168:171], v[220:223], v[16:19]
	s_setprio 0
	s_setprio 1
	v_mfma_f32_16x16x32_bf16 v[44:47], v[172:175], v[192:195], 0
	v_mfma_f32_16x16x32_bf16 v[40:43], v[184:187], v[192:195], 0
	v_mfma_f32_16x16x32_bf16 v[28:31], v[172:175], v[200:203], 0
	v_mfma_f32_16x16x32_bf16 v[24:27], v[184:187], v[200:203], 0
	v_mfma_f32_16x16x32_bf16 v[12:15], v[172:175], v[208:211], 0
	v_mfma_f32_16x16x32_bf16 v[8:11], v[184:187], v[208:211], 0
	v_mfma_f32_16x16x32_bf16 v[4:7], v[172:175], v[216:219], 0
	v_mfma_f32_16x16x32_bf16 v[0:3], v[184:187], v[216:219], 0
	v_mfma_f32_16x16x32_bf16 v[44:47], v[180:183], v[196:199], v[44:47]
	v_mfma_f32_16x16x32_bf16 v[40:43], v[188:191], v[196:199], v[40:43]
	v_mfma_f32_16x16x32_bf16 v[28:31], v[180:183], v[204:207], v[28:31]
	v_mfma_f32_16x16x32_bf16 v[24:27], v[188:191], v[204:207], v[24:27]
	v_mfma_f32_16x16x32_bf16 v[12:15], v[180:183], v[212:215], v[12:15]
	v_mfma_f32_16x16x32_bf16 v[8:11], v[188:191], v[212:215], v[8:11]
	v_mfma_f32_16x16x32_bf16 v[4:7], v[180:183], v[220:223], v[4:7]
	v_mfma_f32_16x16x32_bf16 v[0:3], v[188:191], v[220:223], v[0:3]
	s_setprio 0
	s_barrier
	s_branch .Lgemm_join_962

; #define PG8_STAGE(bufoff, gbase, voff) do { _Pragma("unroll") for (int _i = 0; _i < 2; ++_i) \
;         __builtin_amdgcn_global_load_lds((const unsigned*)((const char*)(gbase) + (voff)[_i]), (LAS unsigned*)(lds + (bufoff) + ldsw + _i * 8192), 16, 0, 0); } while (0)
; #define PG8_LDA(dst, b, h) do { _Pragma("unroll") for (int m = 0; m < 4; ++m) _Pragma("unroll") for (int k = 0; k < 2; ++k) dst[m][k] = *(const LAS bf16x8*)(lds + PG8_SA(b, h) + aoff + m * 2048 + k * 1024); } while (0)
; #define PG8_LDB(dst, b, h) do { _Pragma("unroll") for (int n = 0; n < 2; ++n) _Pragma("unroll") for (int k = 0; k < 2; ++k) dst[n][k] = *(const LAS bf16x8*)(lds + PG8_SB(b, h) + boff + n * 2048 + k * 1024); } while (0)
; #define PG8_MMA(ai, bj, At, Bt) do { __builtin_amdgcn_s_setprio(1); _Pragma("unroll") for (int m = 0; m < 4; ++m) _Pragma("unroll") for (int n = 0; n < 2; ++n) _Pragma("unroll") for (int k = 0; k < 2; ++k) \
;         acc[ai][bj][m][n] = __builtin_amdgcn_mfma_f32_16x16x32_bf16(Bt[n][k], At[m][k], acc[ai][bj][m][n], 0, 0, 0); __builtin_amdgcn_s_setprio(0); } while (0)
; #define PG8_WAIT_V(n) asm volatile("s_waitcnt vmcnt(" #n ")" ::: "memory")
; #define PG8_WAIT_L(n) asm volatile("s_waitcnt lgkmcnt(" #n ")" ::: "memory")
; #define PG8_BAR __builtin_amdgcn_s_barrier()
; #define PG8_SCHED __builtin_amdgcn_sched_barrier(0)
; template <class Epi, class Sched, bool ALIGN_EPI>
; __device__ __forceinline__ void gemm_phase(LAS unsigned char* lds, const int wid, const int lda_, const int ldb_, const int K_, const Sched& S, const Epi& E) {
;     ...
;         const bool has_next = S.next(ui + 1, nxt);
;         const int nt = S.nt(cur);
;         const char* nA = has_next ? S.a(nxt) : cA; const char* nB = has_next ? S.b(nxt) : cB;
; #pragma unroll 1
;         for (int t = 0; t < nt; t += 2) {
;             const bool last = (t == nt - 2);
;             const char* a1 = cA + (size_t)(t + 1) * kstep;
;             const char* a2 = last ? nA : cA + (size_t)(t + 2) * kstep; const char* b2 = last ? nB : cB + (size_t)(t + 2) * kstep;
;             const char* a3 = a2 + kstep; const char* b3 = b2 + kstep;
;             PG8_LDB(B0, 0, 0); PG8_LDB(B1, 0, 1); PG8_SCHED; PG8_LDA(At, 0, 0); PG8_STAGE(PG8_SA(1, 1), a1 + hstepA, voffA);
;             PG8_WAIT_V(8); PG8_WAIT_L(0); PG8_BAR; PG8_MMA(0, 0, At, B0); PG8_MMA(0, 1, At, B1); PG8_BAR; PG8_SCHED;
.LBB0_1119:
	v_mov_b64_e32 v[0:1], s[0:1]
	s_ashr_i32 s45, s44, 31
	v_cmp_lt_i64_e32 vcc, s[4:5], v[0:1]
	s_lshl_b64 s[4:5], s[44:45], 20
	v_readlane_b32 s46, v253, 52
	v_readlane_b32 s47, v253, 53
	s_add_u32 s46, s46, s4
	s_addc_u32 s47, s47, s5
	s_and_b64 s[4:5], vcc, exec
	s_cselect_b32 s4, s47, s41
	s_cselect_b32 s5, s46, s40
	s_ashr_i32 s43, s42, 31
	s_lshl_b64 s[48:49], s[42:43], 20
	s_add_u32 s48, s15, s48
	s_addc_u32 s49, s26, s49
	s_and_b64 s[76:77], vcc, exec
	s_cselect_b32 s43, s49, s51
	s_cselect_b32 s45, s48, s50
	s_add_u32 s76, s40, 0x80
	s_addc_u32 s77, s41, 0
	v_lshl_add_u64 v[156:157], s[76:77], 0, v[152:153]
	v_lshl_add_u64 v[158:159], s[76:77], 0, v[154:155]
	s_add_u32 s76, s50, 0x100
	s_addc_u32 s77, s51, 0
	s_mov_b32 s78, -2
	s_mov_b64 s[50:51], 0
	s_add_u32 s17, s40, s50
	s_addc_u32 s27, s41, s51
	s_add_u32 s17, s17, 0x100
	s_addc_u32 s27, s27, 0
	s_add_u32 s79, s76, s50
	s_addc_u32 s80, s77, s51
	s_add_i32 s86, 0, 0x10000
	s_cmpk_eq_i32 s50, 0xf00
	s_cselect_b32 s95, s4, s27
	s_cselect_b32 s94, s5, s17
	v_add_u32_e32 v141, s86, v135
	s_cselect_b32 s81, s43, s80
	s_cselect_b32 s80, s45, s79
	s_add_i32 s17, 0, 0x14000
	ds_read_b128 v[160:163], v141
	ds_read_b128 v[164:167], v141 offset:1024
	ds_read_b128 v[168:171], v141 offset:2048
	ds_read_b128 v[172:175], v141 offset:3072
	v_add_u32_e32 v141, s17, v135
	ds_read_b128 v[180:183], v141
	ds_read_b128 v[184:187], v141 offset:1024
	ds_read_b128 v[188:191], v141 offset:2048
	ds_read_b128 v[192:195], v141 offset:3072
	v_lshl_add_u64 v[228:229], v[158:159], 0, s[50:51]
	s_add_i32 m0, s16, 0xc000
	ds_read_b128 v[196:199], v139
	ds_read_b128 v[200:203], v139 offset:1024
	ds_read_b128 v[204:207], v139 offset:2048
	ds_read_b128 v[208:211], v139 offset:3072
	ds_read_b128 v[212:215], v139 offset:4096
	ds_read_b128 v[216:219], v139 offset:5120
	ds_read_b128 v[220:223], v139 offset:6144
	ds_read_b128 v[224:227], v139 offset:7168
	global_load_lds_dwordx4 v[228:229], off
	v_lshl_add_u64 v[228:229], v[156:157], 0, s[50:51]
	s_add_i32 m0, s16, 0xe000
	s_nop 0
	global_load_lds_dwordx4 v[228:229], off
	s_waitcnt vmcnt(24)
	s_waitcnt lgkmcnt(0)
	s_barrier
	s_setprio 1
	s_waitcnt lgkmcnt(0)
	v_mfma_f32_16x16x32_bf16 v[124:127], v[160:163], v[196:199], 0
	v_mfma_f32_16x16x32_bf16 v[120:123], v[168:171], v[196:199], 0
	v_mfma_f32_16x16x32_bf16 v[116:119], v[160:163], v[204:207], 0
	v_mfma_f32_16x16x32_bf16 v[112:115], v[168:171], v[204:207], 0
	v_mfma_f32_16x16x32_bf16 v[100:103], v[160:163], v[212:215], 0
	v_mfma_f32_16x16x32_bf16 v[96:99], v[168:171], v[212:215], 0
	v_mfma_f32_16x16x32_bf16 v[84:87], v[160:163], v[220:223], 0
	v_mfma_f32_16x16x32_bf16 v[80:83], v[168:171], v[220:223], 0
	v_mfma_f32_16x16x32_bf16 v[124:127], v[164:167], v[200:203], v[124:127]
	v_mfma_f32_16x16x32_bf16 v[120:123], v[172:175], v[200:203], v[120:123]
	v_mfma_f32_16x16x32_bf16 v[116:119], v[164:167], v[208:211], v[116:119]
	v_mfma_f32_16x16x32_bf16 v[112:115], v[172:175], v[208:211], v[112:115]
	v_mfma_f32_16x16x32_bf16 v[100:103], v[164:167], v[216:219], v[100:103]
	v_mfma_f32_16x16x32_bf16 v[96:99], v[172:175], v[216:219], v[96:99]
	v_mfma_f32_16x16x32_bf16 v[84:87], v[164:167], v[224:227], v[84:87]
	v_mfma_f32_16x16x32_bf16 v[80:83], v[172:175], v[224:227], v[80:83]
	s_setprio 0
	s_setprio 1
	v_mfma_f32_16x16x32_bf16 v[108:111], v[180:183], v[196:199], 0
	v_mfma_f32_16x16x32_bf16 v[104:107], v[188:191], v[196:199], 0
	v_mfma_f32_16x16x32_bf16 v[92:95], v[180:183], v[204:207], 0
	v_mfma_f32_16x16x32_bf16 v[88:91], v[188:191], v[204:207], 0
	v_mfma_f32_16x16x32_bf16 v[76:79], v[180:183], v[212:215], 0
	v_mfma_f32_16x16x32_bf16 v[72:75], v[188:191], v[212:215], 0
	v_mfma_f32_16x16x32_bf16 v[68:71], v[180:183], v[220:223], 0
	v_mfma_f32_16x16x32_bf16 v[64:67], v[188:191], v[220:223], 0
	v_mfma_f32_16x16x32_bf16 v[108:111], v[184:187], v[200:203], v[108:111]
	v_mfma_f32_16x16x32_bf16 v[104:107], v[192:195], v[200:203], v[104:107]
	v_mfma_f32_16x16x32_bf16 v[92:95], v[184:187], v[208:211], v[92:95]
	v_mfma_f32_16x16x32_bf16 v[88:91], v[192:195], v[208:211], v[88:91]
	v_mfma_f32_16x16x32_bf16 v[76:79], v[184:187], v[216:219], v[76:79]
	v_mfma_f32_16x16x32_bf16 v[72:75], v[192:195], v[216:219], v[72:75]
	v_mfma_f32_16x16x32_bf16 v[68:71], v[184:187], v[224:227], v[68:71]
	v_mfma_f32_16x16x32_bf16 v[64:67], v[192:195], v[224:227], v[64:67]
	s_setprio 0
	s_barrier
; #define PG8_STAGE(bufoff, gbase, voff) do { _Pragma("unroll") for (int _i = 0; _i < 2; ++_i) \
;         __builtin_amdgcn_global_load_lds((const unsigned*)((const char*)(gbase) + (voff)[_i]), (LAS unsigned*)(lds + (bufoff) + ldsw + _i * 8192), 16, 0, 0); } while (0)
; #define PG8_LDA(dst, b, h) do { _Pragma("unroll") for (int m = 0; m < 4; ++m) _Pragma("unroll") for (int k = 0; k < 2; ++k) dst[m][k] = *(const LAS bf16x8*)(lds + PG8_SA(b, h) + aoff + m * 2048 + k * 1024); } while (0)
; #define PG8_MMA(ai, bj, At, Bt) do { __builtin_amdgcn_s_setprio(1); _Pragma("unroll") for (int m = 0; m < 4; ++m) _Pragma("unroll") for (int n = 0; n < 2; ++n) _Pragma("unroll") for (int k = 0; k < 2; ++k) \
;         acc[ai][bj][m][n] = __builtin_amdgcn_mfma_f32_16x16x32_bf16(Bt[n][k], At[m][k], acc[ai][bj][m][n], 0, 0, 0); __builtin_amdgcn_s_setprio(0); } while (0)
; #define PG8_WAIT_V(n) asm volatile("s_waitcnt vmcnt(" #n ")" ::: "memory")
; #define PG8_WAIT_L(n) asm volatile("s_waitcnt lgkmcnt(" #n ")" ::: "memory")
; #define PG8_BAR __builtin_amdgcn_s_barrier()
; #define PG8_SCHED __builtin_amdgcn_sched_barrier(0)
; template <class Epi, class Sched, bool ALIGN_EPI>
; __device__ __forceinline__ void gemm_phase(LAS unsigned char* lds, const int wid, const int lda_, const int ldb_, const int K_, const Sched& S, const Epi& E) {
;     ...
;             PG8_LDA(At, 0, 1); PG8_STAGE(PG8_SB(0, 0), b2, voffB); PG8_STAGE(PG8_SB(0, 1), b2 + hstepB, voffB); PG8_STAGE(PG8_SA(0, 0), a2, voffA);
;             PG8_WAIT_V(8); PG8_WAIT_L(0); PG8_BAR; PG8_MMA(1, 0, At, B0); PG8_MMA(1, 1, At, B1); PG8_BAR; PG8_SCHED;
	s_add_i32 s27, s86, s3
	v_lshl_add_u64 v[228:229], s[80:81], 0, v[176:177]
	s_mov_b32 m0, s27
	ds_read_b128 v[196:199], v139 offset:16384
	ds_read_b128 v[200:203], v139 offset:17408
	ds_read_b128 v[204:207], v139 offset:18432
	ds_read_b128 v[208:211], v139 offset:19456
	ds_read_b128 v[212:215], v139 offset:20480
	ds_read_b128 v[216:219], v139 offset:21504
	ds_read_b128 v[220:223], v139 offset:22528
	ds_read_b128 v[224:227], v139 offset:23552
	global_load_lds_dwordx4 v[228:229], off
	s_add_i32 m0, s27, 0x2000
	v_lshl_add_u64 v[230:231], s[80:81], 0, v[128:129]
	s_add_u32 s80, s80, s30
	s_addc_u32 s81, s81, s31
	s_add_i32 s17, s17, s3
	global_load_lds_dwordx4 v[230:231], off
	v_lshl_add_u64 v[232:233], s[80:81], 0, v[176:177]
	s_mov_b32 m0, s17
	v_lshl_add_u64 v[234:235], s[80:81], 0, v[128:129]
	global_load_lds_dwordx4 v[232:233], off
	s_add_i32 m0, s17, 0x2000
	v_lshl_add_u64 v[236:237], s[94:95], 0, v[132:133]
	global_load_lds_dwordx4 v[234:235], off
	s_mov_b32 m0, s16
	v_lshl_add_u64 v[246:247], s[94:95], 0, v[130:131]
	global_load_lds_dwordx4 v[236:237], off
	s_mov_b32 m0, s35
	s_nop 0
	global_load_lds_dwordx4 v[246:247], off
	s_waitcnt vmcnt(24)
	s_waitcnt lgkmcnt(0)
	s_barrier
	s_setprio 1
	s_waitcnt lgkmcnt(0)
	v_mfma_f32_16x16x32_bf16 v[60:63], v[160:163], v[196:199], 0
	v_mfma_f32_16x16x32_bf16 v[56:59], v[168:171], v[196:199], 0
	v_mfma_f32_16x16x32_bf16 v[52:55], v[160:163], v[204:207], 0
	v_mfma_f32_16x16x32_bf16 v[48:51], v[168:171], v[204:207], 0
	v_mfma_f32_16x16x32_bf16 v[36:39], v[160:163], v[212:215], 0
	v_mfma_f32_16x16x32_bf16 v[32:35], v[168:171], v[212:215], 0
	v_mfma_f32_16x16x32_bf16 v[20:23], v[160:163], v[220:223], 0
	v_mfma_f32_16x16x32_bf16 v[16:19], v[168:171], v[220:223], 0
	v_mfma_f32_16x16x32_bf16 v[60:63], v[164:167], v[200:203], v[60:63]
	v_mfma_f32_16x16x32_bf16 v[56:59], v[172:175], v[200:203], v[56:59]
	v_mfma_f32_16x16x32_bf16 v[52:55], v[164:167], v[208:211], v[52:55]
	v_mfma_f32_16x16x32_bf16 v[48:51], v[172:175], v[208:211], v[48:51]
	v_mfma_f32_16x16x32_bf16 v[36:39], v[164:167], v[216:219], v[36:39]
	v_mfma_f32_16x16x32_bf16 v[32:35], v[172:175], v[216:219], v[32:35]
	v_mfma_f32_16x16x32_bf16 v[20:23], v[164:167], v[224:227], v[20:23]
	v_mfma_f32_16x16x32_bf16 v[16:19], v[172:175], v[224:227], v[16:19]
	s_setprio 0
	s_setprio 1
	v_mfma_f32_16x16x32_bf16 v[44:47], v[180:183], v[196:199], 0
	v_mfma_f32_16x16x32_bf16 v[40:43], v[188:191], v[196:199], 0
	v_mfma_f32_16x16x32_bf16 v[28:31], v[180:183], v[204:207], 0
	v_mfma_f32_16x16x32_bf16 v[24:27], v[188:191], v[204:207], 0
	v_mfma_f32_16x16x32_bf16 v[12:15], v[180:183], v[212:215], 0
	v_mfma_f32_16x16x32_bf16 v[8:11], v[188:191], v[212:215], 0
	v_mfma_f32_16x16x32_bf16 v[4:7], v[180:183], v[220:223], 0
	v_mfma_f32_16x16x32_bf16 v[0:3], v[188:191], v[220:223], 0
	v_mfma_f32_16x16x32_bf16 v[44:47], v[184:187], v[200:203], v[44:47]
	v_mfma_f32_16x16x32_bf16 v[40:43], v[192:195], v[200:203], v[40:43]
	v_mfma_f32_16x16x32_bf16 v[28:31], v[184:187], v[208:211], v[28:31]
	v_mfma_f32_16x16x32_bf16 v[24:27], v[192:195], v[208:211], v[24:27]
	v_mfma_f32_16x16x32_bf16 v[12:15], v[184:187], v[216:219], v[12:15]
	v_mfma_f32_16x16x32_bf16 v[8:11], v[192:195], v[216:219], v[8:11]
	v_mfma_f32_16x16x32_bf16 v[4:7], v[184:187], v[224:227], v[4:7]
	v_mfma_f32_16x16x32_bf16 v[0:3], v[192:195], v[224:227], v[0:3]
	s_setprio 0
	s_barrier
	s_branch .Lgemm_join_1120

; #define PG8_STAGE(bufoff, gbase, voff) do { _Pragma("unroll") for (int _i = 0; _i < 2; ++_i) \
;         __builtin_amdgcn_global_load_lds((const unsigned*)((const char*)(gbase) + (voff)[_i]), (LAS unsigned*)(lds + (bufoff) + ldsw + _i * 8192), 16, 0, 0); } while (0)
; #define PG8_LDA(dst, b, h) do { _Pragma("unroll") for (int m = 0; m < 4; ++m) _Pragma("unroll") for (int k = 0; k < 2; ++k) dst[m][k] = *(const LAS bf16x8*)(lds + PG8_SA(b, h) + aoff + m * 2048 + k * 1024); } while (0)
; #define PG8_LDB(dst, b, h) do { _Pragma("unroll") for (int n = 0; n < 2; ++n) _Pragma("unroll") for (int k = 0; k < 2; ++k) dst[n][k] = *(const LAS bf16x8*)(lds + PG8_SB(b, h) + boff + n * 2048 + k * 1024); } while (0)
; #define PG8_MMA(ai, bj, At, Bt) do { __builtin_amdgcn_s_setprio(1); _Pragma("unroll") for (int m = 0; m < 4; ++m) _Pragma("unroll") for (int n = 0; n < 2; ++n) _Pragma("unroll") for (int k = 0; k < 2; ++k) \
;         acc[ai][bj][m][n] = __builtin_amdgcn_mfma_f32_16x16x32_bf16(Bt[n][k], At[m][k], acc[ai][bj][m][n], 0, 0, 0); __builtin_amdgcn_s_setprio(0); } while (0)
; #define PG8_WAIT_V(n) asm volatile("s_waitcnt vmcnt(" #n ")" ::: "memory")
; #define PG8_WAIT_L(n) asm volatile("s_waitcnt lgkmcnt(" #n ")" ::: "memory")
; #define PG8_BAR __builtin_amdgcn_s_barrier()
; #define PG8_SCHED __builtin_amdgcn_sched_barrier(0)
; template <class Epi, class Sched, bool ALIGN_EPI>
; __device__ __forceinline__ void gemm_phase(LAS unsigned char* lds, const int wid, const int lda_, const int ldb_, const int K_, const Sched& S, const Epi& E) {
;     ...
;         const bool has_next = S.next(ui + 1, nxt);
;         const int nt = S.nt(cur);
;         const char* nA = has_next ? S.a(nxt) : cA; const char* nB = has_next ? S.b(nxt) : cB;
; #pragma unroll 1
;         for (int t = 0; t < nt; t += 2) {
;             const bool last = (t == nt - 2);
;             const char* a1 = cA + (size_t)(t + 1) * kstep;
;             const char* a2 = last ? nA : cA + (size_t)(t + 2) * kstep; const char* b2 = last ? nB : cB + (size_t)(t + 2) * kstep;
;             const char* a3 = a2 + kstep; const char* b3 = b2 + kstep;
;             PG8_LDB(B0, 0, 0); PG8_LDB(B1, 0, 1); PG8_SCHED; PG8_LDA(At, 0, 0); PG8_STAGE(PG8_SA(1, 1), a1 + hstepA, voffA);
;             PG8_WAIT_V(8); PG8_WAIT_L(0); PG8_BAR; PG8_MMA(0, 0, At, B0); PG8_MMA(0, 1, At, B1); PG8_BAR; PG8_SCHED;
.LBB0_1340:
	s_cmp_gt_i32 s38, -1
	s_cselect_b64 s[44:45], -1, 0
	s_cmp_lt_i32 s38, 0
	s_cselect_b32 s4, 0x58, 22
	s_add_i32 s5, s4, -2
	s_add_u32 s46, s46, 0x80
	s_addc_u32 s47, s47, 0
	s_add_u32 s31, s48, 0x100
	s_mov_b32 s39, 0
	s_addc_u32 s35, s49, 0
	s_add_i32 s76, s39, 2
	s_add_u32 s17, s46, 0x80
	s_addc_u32 s27, s47, 0
	s_add_i32 s77, 0, 0x10000
	s_cmp_eq_u32 s5, s39
	s_cselect_b32 s49, s43, s27
	s_cselect_b32 s48, s42, s17
	v_add_u32_e32 v141, s77, v135
	s_cselect_b32 s79, s37, s35
	s_cselect_b32 s78, s36, s31
	s_add_i32 s17, 0, 0x14000
	ds_read_b128 v[156:159], v141
	ds_read_b128 v[160:163], v141 offset:1024
	ds_read_b128 v[164:167], v141 offset:2048
	ds_read_b128 v[168:171], v141 offset:3072
	v_add_u32_e32 v141, s17, v135
	ds_read_b128 v[172:175], v141
	ds_read_b128 v[180:183], v141 offset:1024
	ds_read_b128 v[184:187], v141 offset:2048
	ds_read_b128 v[188:191], v141 offset:3072
	v_lshl_add_u64 v[224:225], s[46:47], 0, v[152:153]
	s_add_i32 m0, s16, 0xc000
	ds_read_b128 v[192:195], v139
	ds_read_b128 v[196:199], v139 offset:1024
	ds_read_b128 v[200:203], v139 offset:2048
	ds_read_b128 v[204:207], v139 offset:3072
	ds_read_b128 v[208:211], v139 offset:4096
	ds_read_b128 v[212:215], v139 offset:5120
	ds_read_b128 v[216:219], v139 offset:6144
	ds_read_b128 v[220:223], v139 offset:7168
	global_load_lds_dwordx4 v[224:225], off
	v_lshl_add_u64 v[224:225], s[46:47], 0, v[154:155]
	s_add_i32 m0, s16, 0xe000
	s_nop 0
	global_load_lds_dwordx4 v[224:225], off
	s_waitcnt vmcnt(24)
	s_waitcnt lgkmcnt(0)
	s_barrier
	s_setprio 1
	s_waitcnt lgkmcnt(0)
	v_mfma_f32_16x16x32_bf16 v[124:127], v[156:159], v[192:195], 0
	v_mfma_f32_16x16x32_bf16 v[120:123], v[164:167], v[192:195], 0
	v_mfma_f32_16x16x32_bf16 v[116:119], v[156:159], v[200:203], 0
	v_mfma_f32_16x16x32_bf16 v[112:115], v[164:167], v[200:203], 0
	v_mfma_f32_16x16x32_bf16 v[100:103], v[156:159], v[208:211], 0
	v_mfma_f32_16x16x32_bf16 v[96:99], v[164:167], v[208:211], 0
	v_mfma_f32_16x16x32_bf16 v[84:87], v[156:159], v[216:219], 0
	v_mfma_f32_16x16x32_bf16 v[80:83], v[164:167], v[216:219], 0
	v_mfma_f32_16x16x32_bf16 v[124:127], v[160:163], v[196:199], v[124:127]
	v_mfma_f32_16x16x32_bf16 v[120:123], v[168:171], v[196:199], v[120:123]
	v_mfma_f32_16x16x32_bf16 v[116:119], v[160:163], v[204:207], v[116:119]
	v_mfma_f32_16x16x32_bf16 v[112:115], v[168:171], v[204:207], v[112:115]
	v_mfma_f32_16x16x32_bf16 v[100:103], v[160:163], v[212:215], v[100:103]
	v_mfma_f32_16x16x32_bf16 v[96:99], v[168:171], v[212:215], v[96:99]
	v_mfma_f32_16x16x32_bf16 v[84:87], v[160:163], v[220:223], v[84:87]
	v_mfma_f32_16x16x32_bf16 v[80:83], v[168:171], v[220:223], v[80:83]
	s_setprio 0
	s_setprio 1
	v_mfma_f32_16x16x32_bf16 v[108:111], v[172:175], v[192:195], 0
	v_mfma_f32_16x16x32_bf16 v[104:107], v[184:187], v[192:195], 0
	v_mfma_f32_16x16x32_bf16 v[92:95], v[172:175], v[200:203], 0
	v_mfma_f32_16x16x32_bf16 v[88:91], v[184:187], v[200:203], 0
	v_mfma_f32_16x16x32_bf16 v[76:79], v[172:175], v[208:211], 0
	v_mfma_f32_16x16x32_bf16 v[72:75], v[184:187], v[208:211], 0
	v_mfma_f32_16x16x32_bf16 v[68:71], v[172:175], v[216:219], 0
	v_mfma_f32_16x16x32_bf16 v[64:67], v[184:187], v[216:219], 0
	v_mfma_f32_16x16x32_bf16 v[108:111], v[180:183], v[196:199], v[108:111]
	v_mfma_f32_16x16x32_bf16 v[104:107], v[188:191], v[196:199], v[104:107]
	v_mfma_f32_16x16x32_bf16 v[92:95], v[180:183], v[204:207], v[92:95]
	v_mfma_f32_16x16x32_bf16 v[88:91], v[188:191], v[204:207], v[88:91]
	v_mfma_f32_16x16x32_bf16 v[76:79], v[180:183], v[212:215], v[76:79]
	v_mfma_f32_16x16x32_bf16 v[72:75], v[188:191], v[212:215], v[72:75]
	v_mfma_f32_16x16x32_bf16 v[68:71], v[180:183], v[220:223], v[68:71]
	v_mfma_f32_16x16x32_bf16 v[64:67], v[188:191], v[220:223], v[64:67]
	s_setprio 0
	s_barrier
; #define PG8_STAGE(bufoff, gbase, voff) do { _Pragma("unroll") for (int _i = 0; _i < 2; ++_i) \
;         __builtin_amdgcn_global_load_lds((const unsigned*)((const char*)(gbase) + (voff)[_i]), (LAS unsigned*)(lds + (bufoff) + ldsw + _i * 8192), 16, 0, 0); } while (0)
; #define PG8_LDA(dst, b, h) do { _Pragma("unroll") for (int m = 0; m < 4; ++m) _Pragma("unroll") for (int k = 0; k < 2; ++k) dst[m][k] = *(const LAS bf16x8*)(lds + PG8_SA(b, h) + aoff + m * 2048 + k * 1024); } while (0)
; #define PG8_MMA(ai, bj, At, Bt) do { __builtin_amdgcn_s_setprio(1); _Pragma("unroll") for (int m = 0; m < 4; ++m) _Pragma("unroll") for (int n = 0; n < 2; ++n) _Pragma("unroll") for (int k = 0; k < 2; ++k) \
;         acc[ai][bj][m][n] = __builtin_amdgcn_mfma_f32_16x16x32_bf16(Bt[n][k], At[m][k], acc[ai][bj][m][n], 0, 0, 0); __builtin_amdgcn_s_setprio(0); } while (0)
; #define PG8_WAIT_V(n) asm volatile("s_waitcnt vmcnt(" #n ")" ::: "memory")
; #define PG8_WAIT_L(n) asm volatile("s_waitcnt lgkmcnt(" #n ")" ::: "memory")
; #define PG8_BAR __builtin_amdgcn_s_barrier()
; #define PG8_SCHED __builtin_amdgcn_sched_barrier(0)
; template <class Epi, class Sched, bool ALIGN_EPI>
; __device__ __forceinline__ void gemm_phase(LAS unsigned char* lds, const int wid, const int lda_, const int ldb_, const int K_, const Sched& S, const Epi& E) {
;     ...
;             PG8_LDA(At, 0, 1); PG8_STAGE(PG8_SB(0, 0), b2, voffB); PG8_STAGE(PG8_SB(0, 1), b2 + hstepB, voffB); PG8_STAGE(PG8_SA(0, 0), a2, voffA);
;             PG8_WAIT_V(8); PG8_WAIT_L(0); PG8_BAR; PG8_MMA(1, 0, At, B0); PG8_MMA(1, 1, At, B1); PG8_BAR; PG8_SCHED;
	s_add_i32 s27, s77, s3
	v_lshl_add_u64 v[224:225], s[78:79], 0, v[176:177]
	s_mov_b32 m0, s27
	ds_read_b128 v[192:195], v139 offset:16384
	ds_read_b128 v[196:199], v139 offset:17408
	ds_read_b128 v[200:203], v139 offset:18432
	ds_read_b128 v[204:207], v139 offset:19456
	ds_read_b128 v[208:211], v139 offset:20480
	ds_read_b128 v[212:215], v139 offset:21504
	ds_read_b128 v[216:219], v139 offset:22528
	ds_read_b128 v[220:223], v139 offset:23552
	global_load_lds_dwordx4 v[224:225], off
	s_add_i32 m0, s27, 0x2000
	v_lshl_add_u64 v[226:227], s[78:79], 0, v[132:133]
	s_add_u32 s78, s78, s10
	s_addc_u32 s79, s79, s11
	s_add_i32 s17, s17, s3
	global_load_lds_dwordx4 v[226:227], off
	v_lshl_add_u64 v[228:229], s[78:79], 0, v[176:177]
	s_mov_b32 m0, s17
	v_lshl_add_u64 v[230:231], s[78:79], 0, v[132:133]
	global_load_lds_dwordx4 v[228:229], off
	s_add_i32 m0, s17, 0x2000
	v_lshl_add_u64 v[232:233], s[48:49], 0, v[128:129]
	global_load_lds_dwordx4 v[230:231], off
	s_mov_b32 m0, s16
	v_lshl_add_u64 v[234:235], s[48:49], 0, v[130:131]
	global_load_lds_dwordx4 v[232:233], off
	s_mov_b32 m0, s14
	s_nop 0
	global_load_lds_dwordx4 v[234:235], off
	s_waitcnt vmcnt(24)
	s_waitcnt lgkmcnt(0)
	s_barrier
	s_setprio 1
	s_waitcnt lgkmcnt(0)
	v_mfma_f32_16x16x32_bf16 v[60:63], v[156:159], v[192:195], 0
	v_mfma_f32_16x16x32_bf16 v[56:59], v[164:167], v[192:195], 0
	v_mfma_f32_16x16x32_bf16 v[52:55], v[156:159], v[200:203], 0
	v_mfma_f32_16x16x32_bf16 v[48:51], v[164:167], v[200:203], 0
	v_mfma_f32_16x16x32_bf16 v[36:39], v[156:159], v[208:211], 0
	v_mfma_f32_16x16x32_bf16 v[32:35], v[164:167], v[208:211], 0
	v_mfma_f32_16x16x32_bf16 v[20:23], v[156:159], v[216:219], 0
	v_mfma_f32_16x16x32_bf16 v[16:19], v[164:167], v[216:219], 0
	v_mfma_f32_16x16x32_bf16 v[60:63], v[160:163], v[196:199], v[60:63]
	v_mfma_f32_16x16x32_bf16 v[56:59], v[168:171], v[196:199], v[56:59]
	v_mfma_f32_16x16x32_bf16 v[52:55], v[160:163], v[204:207], v[52:55]
	v_mfma_f32_16x16x32_bf16 v[48:51], v[168:171], v[204:207], v[48:51]
	v_mfma_f32_16x16x32_bf16 v[36:39], v[160:163], v[212:215], v[36:39]
	v_mfma_f32_16x16x32_bf16 v[32:35], v[168:171], v[212:215], v[32:35]
	v_mfma_f32_16x16x32_bf16 v[20:23], v[160:163], v[220:223], v[20:23]
	v_mfma_f32_16x16x32_bf16 v[16:19], v[168:171], v[220:223], v[16:19]
	s_setprio 0
	s_setprio 1
	v_mfma_f32_16x16x32_bf16 v[44:47], v[172:175], v[192:195], 0
	v_mfma_f32_16x16x32_bf16 v[40:43], v[184:187], v[192:195], 0
	v_mfma_f32_16x16x32_bf16 v[28:31], v[172:175], v[200:203], 0
	v_mfma_f32_16x16x32_bf16 v[24:27], v[184:187], v[200:203], 0
	v_mfma_f32_16x16x32_bf16 v[12:15], v[172:175], v[208:211], 0
	v_mfma_f32_16x16x32_bf16 v[8:11], v[184:187], v[208:211], 0
	v_mfma_f32_16x16x32_bf16 v[4:7], v[172:175], v[216:219], 0
	v_mfma_f32_16x16x32_bf16 v[0:3], v[184:187], v[216:219], 0
	v_mfma_f32_16x16x32_bf16 v[44:47], v[180:183], v[196:199], v[44:47]
	v_mfma_f32_16x16x32_bf16 v[40:43], v[188:191], v[196:199], v[40:43]
	v_mfma_f32_16x16x32_bf16 v[28:31], v[180:183], v[204:207], v[28:31]
	v_mfma_f32_16x16x32_bf16 v[24:27], v[188:191], v[204:207], v[24:27]
	v_mfma_f32_16x16x32_bf16 v[12:15], v[180:183], v[212:215], v[12:15]
	v_mfma_f32_16x16x32_bf16 v[8:11], v[188:191], v[212:215], v[8:11]
	v_mfma_f32_16x16x32_bf16 v[4:7], v[180:183], v[220:223], v[4:7]
	v_mfma_f32_16x16x32_bf16 v[0:3], v[188:191], v[220:223], v[0:3]
	s_setprio 0
	s_barrier
	s_branch .Lgemm_join_1341
